# NA: four row-sum accumulators (dependent adds four instructions apart)
# baseline (speedup 1.0000x reference)
.Lna_noremap:
	s_and_b32 s11, s8, 3
	s_lshr_b32 s68, s8, 2
	s_lshl_b32 s36, s11, 3
	s_cmp_ge_u32 s11, 2
	s_cselect_b32 s37, 8, 0
	s_add_i32 s66, s36, s37
	s_lshl_b32 s36, s11, 4
	s_sub_i32 s67, s66, s36
	s_mov_b32 s64, 0xffff
	s_mov_b32 s65, 0xffff
	v_and_b32_e32 v216, 31, v0
	v_bfe_u32 v217, v0, 5, 1
	v_mov_b32_e32 v228, 0
	v_mov_b32_e32 v229, 0xf149f2ca
	v_add_u32_e32 v222, s66, v216
	v_mul_u32_u24_e32 v199, 0x90, v222
	v_lshl_add_u32 v199, v217, 4, v199
	v_mul_u32_u24_e32 v200, 0x90, v216
	v_lshl_add_u32 v200, v217, 4, v200
	v_mul_u32_u24_e32 v222, 0x88, v216
	v_lshl_add_u32 v222, v217, 3, v222
	v_add_u32_e32 v202, 0x4800, v222
	s_lshl_b32 s36, s66, 1
	v_add_u32_e32 v201, s36, v202
	v_lshrrev_b32_e32 v222, 3, v0
	v_and_b32_e32 v223, 7, v0
	v_mul_u32_u24_e32 v204, 0x90, v222
	v_lshl_add_u32 v204, v223, 4, v204
	v_mul_u32_u24_e32 v205, 0x88, v222
	v_lshl_add_u32 v205, v223, 4, v205
	v_add_u32_e32 v205, 0x4800, v205
	v_lshlrev_b32_e32 v206, 4, v0
	v_mul_u32_u24_e32 v207, 0x2200, v222
	v_lshl_add_u32 v207, v223, 4, v207
	v_bfe_u32 v224, v0, 4, 1
	v_and_b32_e32 v225, 15, v0
	s_lshl_b32 s36, s68, 1
	v_add_u32_e32 v222, s36, v224
	s_lshl_b32 s36, s11, 4
	v_add_u32_e32 v223, s36, v225
	v_lshl_add_u32 v222, v222, 6, v223
	v_lshlrev_b32_e32 v219, 7, v222
	v_lshl_add_u32 v219, v217, 4, v219
	v_lshlrev_b32_e32 v218, 10, v222
	v_lshl_add_u32 v218, v217, 3, v218
	v_and_b32_e32 v222, 3, v225
	v_add_u32_e32 v223, 1, v222
	v_and_b32_e32 v223, 3, v223
	v_lshl_add_u32 v223, v217, 2, v223
	v_sub_u32_e32 v223, v223, v225
	s_add_i32 s36, s67, 39
	v_add_u32_e32 v223, s36, v223
	v_mul_u32_u24_e32 v226, 84, v224
	v_sub_u32_e32 v223, v223, v226
	v_lshlrev_b32_e32 v223, 2, v223
	v_mul_u32_u24_e32 v222, 5040, v222
	v_add_u32_e32 v208, v222, v223
	v_add_u32_e32 v208, 0x8c00, v208
	s_lshr_b32 s36, s10, 4
	s_and_b32 s37, s10, 15
	s_mul_i32 s38, s36, 0x88000
	s_add_u32 s38, s38, 0x4700000
	s_add_u32 s12, s4, s38
	s_addc_u32 s13, s5, 0
	s_add_u32 s38, s38, 0x1100000
	s_add_u32 s14, s4, s38
	s_addc_u32 s15, s5, 0
	s_add_u32 s16, s12, 0x80000
	s_addc_u32 s17, s13, 0
	s_add_u32 s18, s14, 0x2000
	s_addc_u32 s19, s15, 0
	s_lshl_b32 s40, s68, 1
	s_add_i32 s38, s37, -1
	s_cmp_lt_u32 s38, 14
	s_cselect_b32 s22, 12, 8
	s_cselect_b32 s39, 1, 0
	s_lshl_b32 s41, s37, 2
	s_add_i32 s42, s41, -4
	s_max_i32 s42, s42, 0
	s_min_i32 s42, s42, 56
	s_sub_i32 s42, s42, s39
	s_add_i32 s43, s41, s40
	s_add_i32 s23, s43, -4
	s_max_i32 s23, s23, 0
	s_min_i32 s23, s23, 56
	s_add_i32 s62, s43, -3
	s_max_i32 s62, s62, 0
	s_min_i32 s62, s62, 56
	s_sub_i32 s62, s62, s23
	s_add_i32 s63, s62, 8
	s_sub_i32 s23, s23, s42
	s_sub_i32 s43, s42, s43
	s_add_i32 s43, s43, 7
	s_mul_i32 s25, s43, 0x150
	s_ashr_i32 s43, s42, 31
	s_lshl_b64 s[44:45], s[42:43], 13
	s_add_u32 s12, s12, s44
	s_addc_u32 s13, s13, s45
	s_lshl_b64 s[44:45], s[42:43], 7
	s_add_u32 s14, s14, s44
	s_addc_u32 s15, s15, s45
	s_lshl_b32 s38, s36, 12
	s_lshl_b32 s39, s37, 8
	s_add_u32 s38, s38, s39
	s_lshl_b32 s38, s38, 7
	s_add_u32 s38, s38, 0x6900000
	s_add_u32 s34, s4, s38
	s_addc_u32 s35, s5, 0
	s_lshr_b32 s38, s36, 3
	s_lshl_b32 s38, s38, 12
	s_add_u32 s38, s38, s39
	s_lshl_b32 s38, s38, 10
	s_and_b32 s40, s36, 7
	s_lshl_b32 s40, s40, 7
	s_add_u32 s38, s38, s40
	s_add_u32 s38, s38, 0x8900000
	s_add_u32 s30, s4, s38
	s_addc_u32 s31, s5, 0
	global_load_dwordx4 v[98:101], v219, s[34:35] offset:0
	global_load_dwordx4 v[102:105], v219, s[34:35] offset:32
	global_load_dwordx4 v[106:109], v219, s[34:35] offset:64
	global_load_dwordx4 v[110:113], v219, s[34:35] offset:96
	global_load_dwordx4 v[34:37], v206, s[12:13]
	s_add_u32 s12, s12, 0x2000
	s_addc_u32 s13, s13, 0
	global_load_dwordx4 v[230:233], v206, s[12:13]
	global_load_dwordx4 v[234:237], v207, s[14:15]
	s_add_u32 s12, s12, 0x2000
	s_addc_u32 s13, s13, 0
	s_add_u32 s14, s14, 0x80
	s_addc_u32 s15, s15, 0
	global_load_dwordx4 v[188:191], v206, s[12:13]
	global_load_dwordx4 v[192:195], v207, s[14:15]
	s_add_u32 s12, s12, 0x2000
	s_addc_u32 s13, s13, 0
	s_add_u32 s14, s14, 0x80
	s_addc_u32 s15, s15, 0
	s_mov_b32 s20, 3
	s_mov_b32 s21, 2
	s_lshr_b32 s36, s10, 4
	s_and_b32 s36, s36, 7
	s_mul_i32 s36, s36, 0x744
	s_add_u32 s38, s6, s36
	s_addc_u32 s39, s7, 0
	s_mov_b32 s36, 0xd00e
	v_mov_b32_e32 v222, v0
	v_mul_lo_u32 v223, v222, s36
	v_lshrrev_b32_e32 v223, 26, v223
	v_mul_u32_u24_e32 v224, 1260, v223
	v_sub_u32_e32 v224, v222, v224
	v_mul_u32_u24_e32 v225, 49933, v224
	v_lshrrev_b32_e32 v225, 22, v225
	v_mul_u32_u24_e32 v226, 84, v225
	v_sub_u32_e32 v226, v224, v226
	v_add_u32_e32 v227, 1, v223
	v_and_b32_e32 v227, 3, v227
	v_sub_u32_e32 v226, v226, v227
	v_subrev_u32_e32 v226, 24, v226
	v_cmp_gt_u32_e64 s[40:41], 31, v226
	s_nop 1
	v_cndmask_b32_e64 v227, 0, v226, s[40:41]
	v_mad_u32_u24 v227, v225, 31, v227
	v_lshlrev_b32_e32 v227, 2, v227
	global_load_dword v40, v227, s[38:39]
	v_add_u32_e32 v222, 512, v0
	v_mul_lo_u32 v223, v222, s36
	v_lshrrev_b32_e32 v223, 26, v223
	v_mul_u32_u24_e32 v224, 1260, v223
	v_sub_u32_e32 v224, v222, v224
	v_mul_u32_u24_e32 v225, 49933, v224
	v_lshrrev_b32_e32 v225, 22, v225
	v_mul_u32_u24_e32 v226, 84, v225
	v_sub_u32_e32 v226, v224, v226
	v_add_u32_e32 v227, 1, v223
	v_and_b32_e32 v227, 3, v227
	v_sub_u32_e32 v226, v226, v227
	v_subrev_u32_e32 v226, 24, v226
	v_cmp_gt_u32_e64 s[42:43], 31, v226
	s_nop 1
	v_cndmask_b32_e64 v227, 0, v226, s[42:43]
	v_mad_u32_u24 v227, v225, 31, v227
	v_lshlrev_b32_e32 v227, 2, v227
	global_load_dword v41, v227, s[38:39]
	v_add_u32_e32 v222, 1024, v0
	v_mul_lo_u32 v223, v222, s36
	v_lshrrev_b32_e32 v223, 26, v223
	v_mul_u32_u24_e32 v224, 1260, v223
	v_sub_u32_e32 v224, v222, v224
	v_mul_u32_u24_e32 v225, 49933, v224
	v_lshrrev_b32_e32 v225, 22, v225
	v_mul_u32_u24_e32 v226, 84, v225
	v_sub_u32_e32 v226, v224, v226
	v_add_u32_e32 v227, 1, v223
	v_and_b32_e32 v227, 3, v227
	v_sub_u32_e32 v226, v226, v227
	v_subrev_u32_e32 v226, 24, v226
	v_cmp_gt_u32_e64 s[44:45], 31, v226
	s_nop 1
	v_cndmask_b32_e64 v227, 0, v226, s[44:45]
	v_mad_u32_u24 v227, v225, 31, v227
	v_lshlrev_b32_e32 v227, 2, v227
	global_load_dword v42, v227, s[38:39]
	v_add_u32_e32 v222, 1536, v0
	v_mul_lo_u32 v223, v222, s36
	v_lshrrev_b32_e32 v223, 26, v223
	v_mul_u32_u24_e32 v224, 1260, v223
	v_sub_u32_e32 v224, v222, v224
	v_mul_u32_u24_e32 v225, 49933, v224
	v_lshrrev_b32_e32 v225, 22, v225
	v_mul_u32_u24_e32 v226, 84, v225
	v_sub_u32_e32 v226, v224, v226
	v_add_u32_e32 v227, 1, v223
	v_and_b32_e32 v227, 3, v227
	v_sub_u32_e32 v226, v226, v227
	v_subrev_u32_e32 v226, 24, v226
	v_cmp_gt_u32_e64 s[46:47], 31, v226
	s_nop 1
	v_cndmask_b32_e64 v227, 0, v226, s[46:47]
	v_mad_u32_u24 v227, v225, 31, v227
	v_lshlrev_b32_e32 v227, 2, v227
	global_load_dword v43, v227, s[38:39]
	v_add_u32_e32 v222, 2048, v0
	v_mul_lo_u32 v223, v222, s36
	v_lshrrev_b32_e32 v223, 26, v223
	v_mul_u32_u24_e32 v224, 1260, v223
	v_sub_u32_e32 v224, v222, v224
	v_mul_u32_u24_e32 v225, 49933, v224
	v_lshrrev_b32_e32 v225, 22, v225
	v_mul_u32_u24_e32 v226, 84, v225
	v_sub_u32_e32 v226, v224, v226
	v_add_u32_e32 v227, 1, v223
	v_and_b32_e32 v227, 3, v227
	v_sub_u32_e32 v226, v226, v227
	v_subrev_u32_e32 v226, 24, v226
	v_cmp_gt_u32_e64 s[48:49], 31, v226
	s_nop 1
	v_cndmask_b32_e64 v227, 0, v226, s[48:49]
	v_mad_u32_u24 v227, v225, 31, v227
	v_lshlrev_b32_e32 v227, 2, v227
	global_load_dword v44, v227, s[38:39]
	v_add_u32_e32 v222, 2560, v0
	v_mul_lo_u32 v223, v222, s36
	v_lshrrev_b32_e32 v223, 26, v223
	v_mul_u32_u24_e32 v224, 1260, v223
	v_sub_u32_e32 v224, v222, v224
	v_mul_u32_u24_e32 v225, 49933, v224
	v_lshrrev_b32_e32 v225, 22, v225
	v_mul_u32_u24_e32 v226, 84, v225
	v_sub_u32_e32 v226, v224, v226
	v_add_u32_e32 v227, 1, v223
	v_and_b32_e32 v227, 3, v227
	v_sub_u32_e32 v226, v226, v227
	v_subrev_u32_e32 v226, 24, v226
	v_cmp_gt_u32_e64 s[50:51], 31, v226
	s_nop 1
	v_cndmask_b32_e64 v227, 0, v226, s[50:51]
	v_mad_u32_u24 v227, v225, 31, v227
	v_lshlrev_b32_e32 v227, 2, v227
	global_load_dword v45, v227, s[38:39]
	v_add_u32_e32 v222, 3072, v0
	v_mul_lo_u32 v223, v222, s36
	v_lshrrev_b32_e32 v223, 26, v223
	v_mul_u32_u24_e32 v224, 1260, v223
	v_sub_u32_e32 v224, v222, v224
	v_mul_u32_u24_e32 v225, 49933, v224
	v_lshrrev_b32_e32 v225, 22, v225
	v_mul_u32_u24_e32 v226, 84, v225
	v_sub_u32_e32 v226, v224, v226
	v_add_u32_e32 v227, 1, v223
	v_and_b32_e32 v227, 3, v227
	v_sub_u32_e32 v226, v226, v227
	v_subrev_u32_e32 v226, 24, v226
	v_cmp_gt_u32_e64 s[52:53], 31, v226
	s_nop 1
	v_cndmask_b32_e64 v227, 0, v226, s[52:53]
	v_mad_u32_u24 v227, v225, 31, v227
	v_lshlrev_b32_e32 v227, 2, v227
	global_load_dword v46, v227, s[38:39]
	v_add_u32_e32 v222, 3584, v0
	v_mul_lo_u32 v223, v222, s36
	v_lshrrev_b32_e32 v223, 26, v223
	v_mul_u32_u24_e32 v224, 1260, v223
	v_sub_u32_e32 v224, v222, v224
	v_mul_u32_u24_e32 v225, 49933, v224
	v_lshrrev_b32_e32 v225, 22, v225
	v_mul_u32_u24_e32 v226, 84, v225
	v_sub_u32_e32 v226, v224, v226
	v_add_u32_e32 v227, 1, v223
	v_and_b32_e32 v227, 3, v227
	v_sub_u32_e32 v226, v226, v227
	v_subrev_u32_e32 v226, 24, v226
	v_cmp_gt_u32_e64 s[54:55], 31, v226
	s_nop 1
	v_cndmask_b32_e64 v227, 0, v226, s[54:55]
	v_mad_u32_u24 v227, v225, 31, v227
	v_lshlrev_b32_e32 v227, 2, v227
	global_load_dword v47, v227, s[38:39]
	v_add_u32_e32 v222, 4096, v0
	v_mul_lo_u32 v223, v222, s36
	v_lshrrev_b32_e32 v223, 26, v223
	v_mul_u32_u24_e32 v224, 1260, v223
	v_sub_u32_e32 v224, v222, v224
	v_mul_u32_u24_e32 v225, 49933, v224
	v_lshrrev_b32_e32 v225, 22, v225
	v_mul_u32_u24_e32 v226, 84, v225
	v_sub_u32_e32 v226, v224, v226
	v_add_u32_e32 v227, 1, v223
	v_and_b32_e32 v227, 3, v227
	v_sub_u32_e32 v226, v226, v227
	v_subrev_u32_e32 v226, 24, v226
	v_cmp_gt_u32_e64 s[56:57], 31, v226
	s_nop 1
	v_cndmask_b32_e64 v227, 0, v226, s[56:57]
	v_mad_u32_u24 v227, v225, 31, v227
	v_lshlrev_b32_e32 v227, 2, v227
	global_load_dword v48, v227, s[38:39]
	v_add_u32_e32 v222, 4608, v0
	v_mul_lo_u32 v223, v222, s36
	v_lshrrev_b32_e32 v223, 26, v223
	v_mul_u32_u24_e32 v224, 1260, v223
	v_sub_u32_e32 v224, v222, v224
	v_mul_u32_u24_e32 v225, 49933, v224
	v_lshrrev_b32_e32 v225, 22, v225
	v_mul_u32_u24_e32 v226, 84, v225
	v_sub_u32_e32 v226, v224, v226
	v_add_u32_e32 v227, 1, v223
	v_and_b32_e32 v227, 3, v227
	v_sub_u32_e32 v226, v226, v227
	v_subrev_u32_e32 v226, 24, v226
	v_cmp_gt_u32_e64 s[58:59], 31, v226
	s_nop 1
	v_cndmask_b32_e64 v227, 0, v226, s[58:59]
	v_mad_u32_u24 v227, v225, 31, v227
	v_lshlrev_b32_e32 v227, 2, v227
	global_load_dword v49, v227, s[38:39]
	v_lshlrev_b32_e32 v222, 2, v0
	s_waitcnt vmcnt(0)
	v_mul_f32_e32 v40, 0x3fb8aa3b, v40
	v_cndmask_b32_e64 v40, 0, v40, s[40:41]
	v_mul_f32_e32 v41, 0x3fb8aa3b, v41
	v_cndmask_b32_e64 v41, 0, v41, s[42:43]
	v_mul_f32_e32 v42, 0x3fb8aa3b, v42
	v_cndmask_b32_e64 v42, 0, v42, s[44:45]
	v_mul_f32_e32 v43, 0x3fb8aa3b, v43
	v_cndmask_b32_e64 v43, 0, v43, s[46:47]
	v_mul_f32_e32 v44, 0x3fb8aa3b, v44
	v_cndmask_b32_e64 v44, 0, v44, s[48:49]
	v_mul_f32_e32 v45, 0x3fb8aa3b, v45
	v_cndmask_b32_e64 v45, 0, v45, s[50:51]
	v_mul_f32_e32 v46, 0x3fb8aa3b, v46
	v_cndmask_b32_e64 v46, 0, v46, s[52:53]
	v_mul_f32_e32 v47, 0x3fb8aa3b, v47
	v_cndmask_b32_e64 v47, 0, v47, s[54:55]
	v_mul_f32_e32 v48, 0x3fb8aa3b, v48
	v_cndmask_b32_e64 v48, 0, v48, s[56:57]
	v_mul_f32_e32 v49, 0x3fb8aa3b, v49
	v_cndmask_b32_e64 v49, 0, v49, s[58:59]
	v_cmp_gt_u32_e32 vcc, 432, v0
	ds_write_b32 v222, v40 offset:35840
	ds_write_b32 v222, v41 offset:37888
	ds_write_b32 v222, v42 offset:39936
	ds_write_b32 v222, v43 offset:41984
	ds_write_b32 v222, v44 offset:44032
	ds_write_b32 v222, v45 offset:46080
	ds_write_b32 v222, v46 offset:48128
	ds_write_b32 v222, v47 offset:50176
	ds_write_b32 v222, v48 offset:52224
	s_and_saveexec_b64 s[60:61], vcc
	ds_write_b32 v222, v49 offset:54272
	s_mov_b64 exec, s[60:61]
	v_mov_b32_e32 v2, 0
	v_mov_b32_e32 v3, 0
	v_mov_b32_e32 v4, 0
	v_mov_b32_e32 v5, 0
	v_mov_b32_e32 v6, 0
	v_mov_b32_e32 v7, 0
	v_mov_b32_e32 v8, 0
	v_mov_b32_e32 v9, 0
	v_mov_b32_e32 v10, 0
	v_mov_b32_e32 v11, 0
	v_mov_b32_e32 v12, 0
	v_mov_b32_e32 v13, 0
	v_mov_b32_e32 v14, 0
	v_mov_b32_e32 v15, 0
	v_mov_b32_e32 v16, 0
	v_mov_b32_e32 v17, 0
	v_mov_b32_e32 v18, 0
	v_mov_b32_e32 v19, 0
	v_mov_b32_e32 v20, 0
	v_mov_b32_e32 v21, 0
	v_mov_b32_e32 v22, 0
	v_mov_b32_e32 v23, 0
	v_mov_b32_e32 v24, 0
	v_mov_b32_e32 v25, 0
	v_mov_b32_e32 v26, 0
	v_mov_b32_e32 v27, 0
	v_mov_b32_e32 v28, 0
	v_mov_b32_e32 v29, 0
	v_mov_b32_e32 v30, 0
	v_mov_b32_e32 v31, 0
	v_mov_b32_e32 v32, 0
	v_mov_b32_e32 v33, 0
	v_mov_b32_e32 v212, 0
	v_mov_b32_e32 v213, 0
	v_mov_b32_e32 v214, 0
	v_mov_b32_e32 v178, 0
	v_mov_b32_e32 v179, 0
	v_mov_b32_e32 v220, 0xff7fffff
	v_mov_b32_e32 v221, 0
	s_mov_b64 s[26:27], -1
	v_and_b32_e32 v216, 15, v0
	v_bfe_u32 v217, v0, 5, 1
	s_lshl_b32 s36, s11, 4
	v_add_u32_e32 v222, s36, v216
	v_subrev_u32_e32 v223, 8, v222
	v_med3_i32 v223, v223, 0, 48
	v_lshl_add_u32 v224, v217, 2, s66
	v_sub_u32_e32 v224, v224, v223
	v_add_u32_e32 v225, 0, v224
	v_cmp_gt_u32_e32 vcc, 16, v225
	s_nop 1
	v_cndmask_b32_e32 v114, v229, v228, vcc
	v_add_u32_e32 v225, 1, v224
	v_cmp_gt_u32_e32 vcc, 16, v225
	s_nop 1
	v_cndmask_b32_e32 v115, v229, v228, vcc
	v_add_u32_e32 v225, 2, v224
	v_cmp_gt_u32_e32 vcc, 16, v225
	s_nop 1
	v_cndmask_b32_e32 v116, v229, v228, vcc
	v_add_u32_e32 v225, 3, v224
	v_cmp_gt_u32_e32 vcc, 16, v225
	s_nop 1
	v_cndmask_b32_e32 v117, v229, v228, vcc
	v_add_u32_e32 v225, 8, v224
	v_cmp_gt_u32_e32 vcc, 16, v225
	s_nop 1
	v_cndmask_b32_e32 v118, v229, v228, vcc
	v_add_u32_e32 v225, 9, v224
	v_cmp_gt_u32_e32 vcc, 16, v225
	s_nop 1
	v_cndmask_b32_e32 v119, v229, v228, vcc
	v_add_u32_e32 v225, 10, v224
	v_cmp_gt_u32_e32 vcc, 16, v225
	s_nop 1
	v_cndmask_b32_e32 v120, v229, v228, vcc
	v_add_u32_e32 v225, 11, v224
	v_cmp_gt_u32_e32 vcc, 16, v225
	s_nop 1
	v_cndmask_b32_e32 v121, v229, v228, vcc
	v_add_u32_e32 v225, 16, v224
	v_cmp_gt_u32_e32 vcc, 16, v225
	s_nop 1
	v_cndmask_b32_e32 v122, v229, v228, vcc
	v_add_u32_e32 v225, 17, v224
	v_cmp_gt_u32_e32 vcc, 16, v225
	s_nop 1
	v_cndmask_b32_e32 v123, v229, v228, vcc
	v_add_u32_e32 v225, 18, v224
	v_cmp_gt_u32_e32 vcc, 16, v225
	s_nop 1
	v_cndmask_b32_e32 v124, v229, v228, vcc
	v_add_u32_e32 v225, 19, v224
	v_cmp_gt_u32_e32 vcc, 16, v225
	s_nop 1
	v_cndmask_b32_e32 v125, v229, v228, vcc
	v_add_u32_e32 v225, 24, v224
	v_cmp_gt_u32_e32 vcc, 16, v225
	s_nop 1
	v_cndmask_b32_e32 v126, v229, v228, vcc
	v_add_u32_e32 v225, 25, v224
	v_cmp_gt_u32_e32 vcc, 16, v225
	s_nop 1
	v_cndmask_b32_e32 v127, v229, v228, vcc
	v_add_u32_e32 v225, 26, v224
	v_cmp_gt_u32_e32 vcc, 16, v225
	s_nop 1
	v_cndmask_b32_e32 v128, v229, v228, vcc
	v_add_u32_e32 v225, 27, v224
	v_cmp_gt_u32_e32 vcc, 16, v225
	s_nop 1
	v_cndmask_b32_e32 v129, v229, v228, vcc

.Lna_wloop:
	s_sub_i32 s36, s24, s23
	s_cmp_lt_u32 s36, s63
	s_cselect_b64 s[40:41], -1, 0
	s_add_i32 s36, s36, 1
	s_cmp_lt_u32 s36, 8
	s_cselect_b64 s[44:45], -1, 0
	s_sub_i32 s37, s36, s62
	s_cmp_lt_u32 s37, 8
	s_cselect_b64 s[46:47], -1, 0
	s_and_b64 s[48:49], s[44:45], s[64:65]
	s_andn2_b64 s[38:39], s[46:47], s[64:65]
	s_or_b64 s[48:49], s[48:49], s[38:39]
	s_or_b64 s[42:43], s[44:45], s[46:47]
	s_and_b64 s[44:45], s[44:45], s[46:47]
	s_and_b64 s[44:45], s[44:45], s[40:41]
	s_cmp_eq_u64 s[44:45], 0
	s_cbranch_scc1 .Lna_slow_w1
	ds_read_b128 v[146:149], v199 offset:0
	ds_read_b128 v[150:153], v199 offset:32
	ds_read_b128 v[154:157], v199 offset:64
	ds_read_b128 v[158:161], v199 offset:96
	v_add_u32_e32 v210, s25, v208
	v_exp_f32_e32 v66, v66
	v_exp_f32_e32 v67, v67
	v_exp_f32_e32 v68, v68
	v_exp_f32_e32 v69, v69
	v_add_f32_e32 v213, v213, v66
	v_add_f32_e32 v214, v214, v67
	s_waitcnt lgkmcnt(3)
	v_mfma_f32_32x32x16_bf16 v[34:49], v[146:149], v[98:101], v[114:129]
	ds_read_b64 v[162:163], v201 offset:8704
	ds_read_b64 v[164:165], v201 offset:8720
	v_add_f32_e32 v178, v178, v68
	v_add_f32_e32 v179, v179, v69
	v_exp_f32_e32 v70, v70
	v_exp_f32_e32 v71, v71
	v_exp_f32_e32 v72, v72
	v_exp_f32_e32 v73, v73
	s_waitcnt lgkmcnt(4)
	v_mfma_f32_32x32x16_bf16 v[34:49], v[150:153], v[102:105], v[34:49]
	ds_read_b64 v[166:167], v201 offset:13056
	ds_read_b64 v[168:169], v201 offset:13072
	v_add_f32_e32 v213, v213, v70
	v_add_f32_e32 v214, v214, v71
	v_add_f32_e32 v178, v178, v72
	v_add_f32_e32 v179, v179, v73
	v_cvt_pk_bf16_f32 v66, v66, v67
	v_cvt_pk_bf16_f32 v67, v68, v69
	v_cvt_pk_bf16_f32 v68, v70, v71
	v_cvt_pk_bf16_f32 v69, v72, v73
	s_waitcnt lgkmcnt(5)
	v_mfma_f32_32x32x16_bf16 v[34:49], v[154:157], v[106:109], v[34:49]
	ds_read_b64 v[170:171], v201 offset:8736
	ds_read_b64 v[172:173], v201 offset:8752
	v_exp_f32_e32 v74, v74
	v_exp_f32_e32 v75, v75
	v_exp_f32_e32 v76, v76
	v_exp_f32_e32 v77, v77
	v_add_f32_e32 v213, v213, v74
	s_waitcnt lgkmcnt(6)
	v_mfma_f32_32x32x16_bf16 v[34:49], v[158:161], v[110:113], v[34:49]
	ds_read_b64 v[174:175], v201 offset:13088
	ds_read_b64 v[176:177], v201 offset:13104
	ds_read_b128 v[146:149], v210 offset:0
	ds_read_b128 v[150:153], v210 offset:32
	ds_read_b128 v[154:157], v210 offset:64
	ds_read_b128 v[158:161], v210 offset:96
	v_add_f32_e32 v214, v214, v75
	v_add_f32_e32 v178, v178, v76
	v_add_f32_e32 v179, v179, v77
	v_exp_f32_e32 v78, v78
	v_exp_f32_e32 v79, v79
	v_exp_f32_e32 v80, v80
	s_waitcnt lgkmcnt(10)
	v_mfma_f32_32x32x16_bf16 v[2:17], v[162:165], v[66:69], v[2:17]
	v_exp_f32_e32 v81, v81
	v_add_f32_e32 v213, v213, v78
	v_add_f32_e32 v214, v214, v79
	v_add_f32_e32 v178, v178, v80
	v_add_f32_e32 v179, v179, v81
	v_cvt_pk_bf16_f32 v74, v74, v75
	v_cvt_pk_bf16_f32 v75, v76, v77
	v_cvt_pk_bf16_f32 v76, v78, v79
	s_waitcnt lgkmcnt(8)
	v_mfma_f32_32x32x16_bf16 v[18:33], v[166:169], v[66:69], v[18:33]
	v_cvt_pk_bf16_f32 v77, v80, v81
	s_waitcnt lgkmcnt(0)
	v_add_f32_e32 v34, v34, v146
	v_add_f32_e32 v35, v35, v147
	v_add_f32_e32 v36, v36, v148
	v_add_f32_e32 v37, v37, v149
	v_add_f32_e32 v38, v38, v150
	v_add_f32_e32 v39, v39, v151
	v_add_f32_e32 v40, v40, v152
	v_add_f32_e32 v41, v41, v153
	v_mfma_f32_32x32x16_bf16 v[2:17], v[170:173], v[74:77], v[2:17]
	v_add_f32_e32 v42, v42, v154
	v_add_f32_e32 v43, v43, v155
	v_add_f32_e32 v44, v44, v156
	v_add_f32_e32 v45, v45, v157
	v_add_f32_e32 v46, v46, v158
	v_add_f32_e32 v47, v47, v159
	v_add_f32_e32 v48, v48, v160
	v_add_f32_e32 v49, v49, v161
	v_max3_f32 v216, v34, v35, v36
	v_mfma_f32_32x32x16_bf16 v[18:33], v[174:177], v[74:77], v[18:33]
	s_waitcnt vmcnt(2)
	ds_write_b128 v204, v[230:233] offset:9216
	ds_write_b64 v205, v[234:235] offset:0
	ds_write_b64 v205, v[236:237] offset:8
	global_load_dwordx4 v[230:233], v206, s[12:13]
	s_add_i32 s20, s20, 1
	s_add_u32 s12, s12, 0x2000
	s_addc_u32 s13, s13, 0
	s_cmp_eq_u32 s20, s22
	s_cselect_b32 s12, s16, s12
	s_cselect_b32 s13, s17, s13
	global_load_dwordx4 v[234:237], v207, s[14:15]
	s_add_i32 s21, s21, 1
	s_add_u32 s14, s14, 0x80
	s_addc_u32 s15, s15, 0
	s_cmp_eq_u32 s21, s22
	s_cselect_b32 s14, s18, s14
	s_cselect_b32 s15, s19, s15
	v_max3_f32 v217, v42, v43, v44
	v_max3_f32 v216, v216, v37, v38
	v_max3_f32 v217, v217, v45, v46
	v_max3_f32 v216, v216, v39, v40
	v_max3_f32 v217, v217, v47, v48
	v_max_f32_e32 v216, v216, v41
	v_max_f32_e32 v217, v217, v49
	v_max_f32_e32 v216, v216, v217
	v_cmp_lt_f32_e32 vcc, 4.0, v216
	s_or_b64 s[28:29], vcc, s[26:27]
	s_cmp_lg_u64 s[28:29], 0
	s_cbranch_scc0 .Lna_nr_w1f
	v_mov_b32_e32 v217, v216
	s_nop 1
	v_permlane32_swap_b32_e32 v216, v217
	v_max_f32_e32 v215, v216, v217
	s_nop 15
	v_max_f32_e32 v216, v215, v220
	v_cmp_lt_f32_e32 vcc, 0xf0c9f2ca, v215
	s_nop 1
	v_cndmask_b32_e32 v216, 0, v216, vcc
	v_exp_f32_e64 v217, -v216
	v_add_f32_e32 v212, v212, v216
	v_and_b32_e32 v217, v217, v221
	v_sub_f32_e32 v34, v34, v216
	v_sub_f32_e32 v35, v35, v216
	v_sub_f32_e32 v36, v36, v216
	v_sub_f32_e32 v37, v37, v216
	v_sub_f32_e32 v38, v38, v216
	v_sub_f32_e32 v39, v39, v216
	v_sub_f32_e32 v40, v40, v216
	v_sub_f32_e32 v41, v41, v216
	v_sub_f32_e32 v42, v42, v216
	v_sub_f32_e32 v43, v43, v216
	v_sub_f32_e32 v44, v44, v216
	v_sub_f32_e32 v45, v45, v216
	v_sub_f32_e32 v46, v46, v216
	v_sub_f32_e32 v47, v47, v216
	v_sub_f32_e32 v48, v48, v216
	v_sub_f32_e32 v49, v49, v216
	v_sub_f32_e32 v114, v114, v216
	v_sub_f32_e32 v115, v115, v216
	v_sub_f32_e32 v116, v116, v216
	v_sub_f32_e32 v117, v117, v216
	v_sub_f32_e32 v118, v118, v216
	v_sub_f32_e32 v119, v119, v216
	v_sub_f32_e32 v120, v120, v216
	v_sub_f32_e32 v121, v121, v216
	v_sub_f32_e32 v122, v122, v216
	v_sub_f32_e32 v123, v123, v216
	v_sub_f32_e32 v124, v124, v216
	v_sub_f32_e32 v125, v125, v216
	v_sub_f32_e32 v126, v126, v216
	v_sub_f32_e32 v127, v127, v216
	v_sub_f32_e32 v128, v128, v216
	v_sub_f32_e32 v129, v129, v216
	v_mul_f32_e32 v213, v213, v217
	v_mul_f32_e32 v214, v214, v217
	v_mul_f32_e32 v178, v178, v217
	v_mul_f32_e32 v179, v179, v217
	v_mul_f32_e32 v2, v2, v217
	v_mul_f32_e32 v3, v3, v217
	v_mul_f32_e32 v4, v4, v217
	v_mul_f32_e32 v5, v5, v217
	v_mul_f32_e32 v6, v6, v217
	v_mul_f32_e32 v7, v7, v217
	v_mul_f32_e32 v8, v8, v217
	v_mul_f32_e32 v9, v9, v217
	v_mul_f32_e32 v10, v10, v217
	v_mul_f32_e32 v11, v11, v217
	v_mul_f32_e32 v12, v12, v217
	v_mul_f32_e32 v13, v13, v217
	v_mul_f32_e32 v14, v14, v217
	v_mul_f32_e32 v15, v15, v217
	v_mul_f32_e32 v16, v16, v217
	v_mul_f32_e32 v17, v17, v217
	v_mul_f32_e32 v18, v18, v217
	v_mul_f32_e32 v19, v19, v217
	v_mul_f32_e32 v20, v20, v217
	v_mul_f32_e32 v21, v21, v217
	v_mul_f32_e32 v22, v22, v217
	v_mul_f32_e32 v23, v23, v217
	v_mul_f32_e32 v24, v24, v217
	v_mul_f32_e32 v25, v25, v217
	v_mul_f32_e32 v26, v26, v217
	v_mul_f32_e32 v27, v27, v217
	v_mul_f32_e32 v28, v28, v217
	v_mul_f32_e32 v29, v29, v217
	v_mul_f32_e32 v30, v30, v217
	v_mul_f32_e32 v31, v31, v217
	v_mul_f32_e32 v32, v32, v217
	v_mul_f32_e32 v33, v33, v217
	v_cndmask_b32_e32 v220, v220, v228, vcc
	v_cndmask_b32_e64 v221, v221, -1, vcc
	s_andn2_b64 s[26:27], s[26:27], vcc

.Lna_slow_w1:
	s_cmp_eq_u64 s[40:41], 0
	s_cbranch_scc1 .Lna_sl_a_w1s
	ds_read_b64 v[162:163], v201 offset:8704
	ds_read_b64 v[164:165], v201 offset:8720
	ds_read_b64 v[166:167], v201 offset:13056
	ds_read_b64 v[168:169], v201 offset:13072
	ds_read_b64 v[170:171], v201 offset:8736
	ds_read_b64 v[172:173], v201 offset:8752
	ds_read_b64 v[174:175], v201 offset:13088
	ds_read_b64 v[176:177], v201 offset:13104
	v_exp_f32_e32 v66, v66
	v_exp_f32_e32 v67, v67
	v_exp_f32_e32 v68, v68
	v_exp_f32_e32 v69, v69
	v_add_f32_e32 v213, v213, v66
	v_add_f32_e32 v214, v214, v67
	v_add_f32_e32 v178, v178, v68
	v_add_f32_e32 v179, v179, v69
	v_exp_f32_e32 v70, v70
	v_exp_f32_e32 v71, v71
	v_exp_f32_e32 v72, v72
	v_exp_f32_e32 v73, v73
	v_add_f32_e32 v213, v213, v70
	v_add_f32_e32 v214, v214, v71
	v_add_f32_e32 v178, v178, v72
	v_add_f32_e32 v179, v179, v73
	v_cvt_pk_bf16_f32 v66, v66, v67
	v_cvt_pk_bf16_f32 v67, v68, v69
	v_cvt_pk_bf16_f32 v68, v70, v71
	v_cvt_pk_bf16_f32 v69, v72, v73
	v_exp_f32_e32 v74, v74
	v_exp_f32_e32 v75, v75
	v_exp_f32_e32 v76, v76
	v_exp_f32_e32 v77, v77
	v_add_f32_e32 v213, v213, v74
	v_add_f32_e32 v214, v214, v75
	v_add_f32_e32 v178, v178, v76
	v_add_f32_e32 v179, v179, v77
	v_exp_f32_e32 v78, v78
	v_exp_f32_e32 v79, v79
	v_exp_f32_e32 v80, v80
	v_exp_f32_e32 v81, v81
	v_add_f32_e32 v213, v213, v78
	v_add_f32_e32 v214, v214, v79
	v_add_f32_e32 v178, v178, v80
	v_add_f32_e32 v179, v179, v81
	v_cvt_pk_bf16_f32 v74, v74, v75
	v_cvt_pk_bf16_f32 v75, v76, v77
	v_cvt_pk_bf16_f32 v76, v78, v79
	v_cvt_pk_bf16_f32 v77, v80, v81
	s_nop 1
	s_waitcnt lgkmcnt(6)
	v_mfma_f32_32x32x16_bf16 v[2:17], v[162:165], v[66:69], v[2:17]
	s_waitcnt lgkmcnt(4)
	v_mfma_f32_32x32x16_bf16 v[18:33], v[166:169], v[66:69], v[18:33]
	s_waitcnt lgkmcnt(2)
	v_mfma_f32_32x32x16_bf16 v[2:17], v[170:173], v[74:77], v[2:17]
	s_waitcnt lgkmcnt(0)
	v_mfma_f32_32x32x16_bf16 v[18:33], v[174:177], v[74:77], v[18:33]
.Lna_sl_a_w1s:
	s_waitcnt lgkmcnt(0)
	s_cmp_eq_u64 s[42:43], 0
	s_cbranch_scc1 .Lna_sl_b_w1s
	ds_read_b128 v[146:149], v199 offset:0
	ds_read_b128 v[150:153], v199 offset:32
	ds_read_b128 v[154:157], v199 offset:64
	ds_read_b128 v[158:161], v199 offset:96
	s_waitcnt lgkmcnt(3)
	v_mfma_f32_32x32x16_bf16 v[34:49], v[146:149], v[98:101], v[114:129]
	s_waitcnt lgkmcnt(2)
	v_mfma_f32_32x32x16_bf16 v[34:49], v[150:153], v[102:105], v[34:49]
	s_waitcnt lgkmcnt(1)
	v_mfma_f32_32x32x16_bf16 v[34:49], v[154:157], v[106:109], v[34:49]
	s_waitcnt lgkmcnt(0)
	v_mfma_f32_32x32x16_bf16 v[34:49], v[158:161], v[110:113], v[34:49]
	v_add_u32_e32 v210, s25, v208
	ds_read_b128 v[146:149], v210 offset:0
	ds_read_b128 v[150:153], v210 offset:32
	ds_read_b128 v[154:157], v210 offset:64
	ds_read_b128 v[158:161], v210 offset:96
	s_waitcnt lgkmcnt(0)
	s_nop 15
	v_add_f32_e32 v34, v34, v146
	v_add_f32_e32 v35, v35, v147
	v_add_f32_e32 v36, v36, v148
	v_add_f32_e32 v37, v37, v149
	v_add_f32_e32 v38, v38, v150
	v_add_f32_e32 v39, v39, v151
	v_add_f32_e32 v40, v40, v152
	v_add_f32_e32 v41, v41, v153
	v_add_f32_e32 v42, v42, v154
	v_add_f32_e32 v43, v43, v155
	v_add_f32_e32 v44, v44, v156
	v_add_f32_e32 v45, v45, v157
	v_add_f32_e32 v46, v46, v158
	v_add_f32_e32 v47, v47, v159
	v_add_f32_e32 v48, v48, v160
	v_add_f32_e32 v49, v49, v161
	v_cndmask_b32_e64 v34, v229, v34, s[48:49]
	v_cndmask_b32_e64 v35, v229, v35, s[48:49]
	v_cndmask_b32_e64 v36, v229, v36, s[48:49]
	v_cndmask_b32_e64 v37, v229, v37, s[48:49]
	v_cndmask_b32_e64 v38, v229, v38, s[48:49]
	v_cndmask_b32_e64 v39, v229, v39, s[48:49]
	v_cndmask_b32_e64 v40, v229, v40, s[48:49]
	v_cndmask_b32_e64 v41, v229, v41, s[48:49]
	v_cndmask_b32_e64 v42, v229, v42, s[48:49]
	v_cndmask_b32_e64 v43, v229, v43, s[48:49]
	v_cndmask_b32_e64 v44, v229, v44, s[48:49]
	v_cndmask_b32_e64 v45, v229, v45, s[48:49]
	v_cndmask_b32_e64 v46, v229, v46, s[48:49]
	v_cndmask_b32_e64 v47, v229, v47, s[48:49]
	v_cndmask_b32_e64 v48, v229, v48, s[48:49]
	v_cndmask_b32_e64 v49, v229, v49, s[48:49]
	v_max3_f32 v216, v34, v35, v36
	v_max3_f32 v217, v42, v43, v44
	v_max3_f32 v216, v216, v37, v38
	v_max3_f32 v217, v217, v45, v46
	v_max3_f32 v216, v216, v39, v40
	v_max3_f32 v217, v217, v47, v48
	v_max_f32_e32 v216, v216, v41
	v_max_f32_e32 v217, v217, v49
	v_max_f32_e32 v216, v216, v217
	v_cmp_lt_f32_e32 vcc, 4.0, v216
	s_or_b64 s[28:29], vcc, s[26:27]
	s_cmp_lg_u64 s[28:29], 0
	s_cbranch_scc0 .Lna_nr_w1s
	v_mov_b32_e32 v217, v216
	s_nop 1
	v_permlane32_swap_b32_e32 v216, v217
	v_max_f32_e32 v215, v216, v217
	s_nop 15
	v_max_f32_e32 v216, v215, v220
	v_cmp_lt_f32_e32 vcc, 0xf0c9f2ca, v215
	s_nop 1
	v_cndmask_b32_e32 v216, 0, v216, vcc
	v_exp_f32_e64 v217, -v216
	v_add_f32_e32 v212, v212, v216
	v_and_b32_e32 v217, v217, v221
	v_sub_f32_e32 v34, v34, v216
	v_sub_f32_e32 v35, v35, v216
	v_sub_f32_e32 v36, v36, v216
	v_sub_f32_e32 v37, v37, v216
	v_sub_f32_e32 v38, v38, v216
	v_sub_f32_e32 v39, v39, v216
	v_sub_f32_e32 v40, v40, v216
	v_sub_f32_e32 v41, v41, v216
	v_sub_f32_e32 v42, v42, v216
	v_sub_f32_e32 v43, v43, v216
	v_sub_f32_e32 v44, v44, v216
	v_sub_f32_e32 v45, v45, v216
	v_sub_f32_e32 v46, v46, v216
	v_sub_f32_e32 v47, v47, v216
	v_sub_f32_e32 v48, v48, v216
	v_sub_f32_e32 v49, v49, v216
	v_sub_f32_e32 v114, v114, v216
	v_sub_f32_e32 v115, v115, v216
	v_sub_f32_e32 v116, v116, v216
	v_sub_f32_e32 v117, v117, v216
	v_sub_f32_e32 v118, v118, v216
	v_sub_f32_e32 v119, v119, v216
	v_sub_f32_e32 v120, v120, v216
	v_sub_f32_e32 v121, v121, v216
	v_sub_f32_e32 v122, v122, v216
	v_sub_f32_e32 v123, v123, v216
	v_sub_f32_e32 v124, v124, v216
	v_sub_f32_e32 v125, v125, v216
	v_sub_f32_e32 v126, v126, v216
	v_sub_f32_e32 v127, v127, v216
	v_sub_f32_e32 v128, v128, v216
	v_sub_f32_e32 v129, v129, v216
	v_mul_f32_e32 v213, v213, v217
	v_mul_f32_e32 v214, v214, v217
	v_mul_f32_e32 v178, v178, v217
	v_mul_f32_e32 v179, v179, v217
	v_mul_f32_e32 v2, v2, v217
	v_mul_f32_e32 v3, v3, v217
	v_mul_f32_e32 v4, v4, v217
	v_mul_f32_e32 v5, v5, v217
	v_mul_f32_e32 v6, v6, v217
	v_mul_f32_e32 v7, v7, v217
	v_mul_f32_e32 v8, v8, v217
	v_mul_f32_e32 v9, v9, v217
	v_mul_f32_e32 v10, v10, v217
	v_mul_f32_e32 v11, v11, v217
	v_mul_f32_e32 v12, v12, v217
	v_mul_f32_e32 v13, v13, v217
	v_mul_f32_e32 v14, v14, v217
	v_mul_f32_e32 v15, v15, v217
	v_mul_f32_e32 v16, v16, v217
	v_mul_f32_e32 v17, v17, v217
	v_mul_f32_e32 v18, v18, v217
	v_mul_f32_e32 v19, v19, v217
	v_mul_f32_e32 v20, v20, v217
	v_mul_f32_e32 v21, v21, v217
	v_mul_f32_e32 v22, v22, v217
	v_mul_f32_e32 v23, v23, v217
	v_mul_f32_e32 v24, v24, v217
	v_mul_f32_e32 v25, v25, v217
	v_mul_f32_e32 v26, v26, v217
	v_mul_f32_e32 v27, v27, v217
	v_mul_f32_e32 v28, v28, v217
	v_mul_f32_e32 v29, v29, v217
	v_mul_f32_e32 v30, v30, v217
	v_mul_f32_e32 v31, v31, v217
	v_mul_f32_e32 v32, v32, v217
	v_mul_f32_e32 v33, v33, v217
	v_cndmask_b32_e32 v220, v220, v228, vcc
	v_cndmask_b32_e64 v221, v221, -1, vcc
	s_andn2_b64 s[26:27], s[26:27], vcc

.Lna_done_w1:
	s_add_i32 s24, s24, 1
	s_add_i32 s25, s25, 0x150
	s_sub_i32 s36, s24, s23
	s_cmp_lt_u32 s36, s63
	s_cselect_b64 s[40:41], -1, 0
	s_add_i32 s36, s36, 1
	s_cmp_lt_u32 s36, 8
	s_cselect_b64 s[44:45], -1, 0
	s_sub_i32 s37, s36, s62
	s_cmp_lt_u32 s37, 8
	s_cselect_b64 s[46:47], -1, 0
	s_and_b64 s[48:49], s[44:45], s[64:65]
	s_andn2_b64 s[38:39], s[46:47], s[64:65]
	s_or_b64 s[48:49], s[48:49], s[38:39]
	s_or_b64 s[42:43], s[44:45], s[46:47]
	s_and_b64 s[44:45], s[44:45], s[46:47]
	s_and_b64 s[44:45], s[44:45], s[40:41]
	s_cmp_eq_u64 s[44:45], 0
	s_cbranch_scc1 .Lna_slow_w0
	ds_read_b128 v[146:149], v199 offset:9216
	ds_read_b128 v[150:153], v199 offset:9248
	ds_read_b128 v[154:157], v199 offset:9280
	ds_read_b128 v[158:161], v199 offset:9312
	v_add_u32_e32 v210, s25, v208
	v_exp_f32_e32 v34, v34
	v_exp_f32_e32 v35, v35
	v_exp_f32_e32 v36, v36
	v_exp_f32_e32 v37, v37
	v_add_f32_e32 v213, v213, v34
	v_add_f32_e32 v214, v214, v35
	s_waitcnt lgkmcnt(3)
	v_mfma_f32_32x32x16_bf16 v[66:81], v[146:149], v[98:101], v[114:129]
	ds_read_b64 v[162:163], v201 offset:0
	ds_read_b64 v[164:165], v201 offset:16
	v_add_f32_e32 v178, v178, v36
	v_add_f32_e32 v179, v179, v37
	v_exp_f32_e32 v38, v38
	v_exp_f32_e32 v39, v39
	v_exp_f32_e32 v40, v40
	v_exp_f32_e32 v41, v41
	s_waitcnt lgkmcnt(4)
	v_mfma_f32_32x32x16_bf16 v[66:81], v[150:153], v[102:105], v[66:81]
	ds_read_b64 v[166:167], v201 offset:4352
	ds_read_b64 v[168:169], v201 offset:4368
	v_add_f32_e32 v213, v213, v38
	v_add_f32_e32 v214, v214, v39
	v_add_f32_e32 v178, v178, v40
	v_add_f32_e32 v179, v179, v41
	v_cvt_pk_bf16_f32 v34, v34, v35
	v_cvt_pk_bf16_f32 v35, v36, v37
	v_cvt_pk_bf16_f32 v36, v38, v39
	v_cvt_pk_bf16_f32 v37, v40, v41
	s_waitcnt lgkmcnt(5)
	v_mfma_f32_32x32x16_bf16 v[66:81], v[154:157], v[106:109], v[66:81]
	ds_read_b64 v[170:171], v201 offset:32
	ds_read_b64 v[172:173], v201 offset:48
	v_exp_f32_e32 v42, v42
	v_exp_f32_e32 v43, v43
	v_exp_f32_e32 v44, v44
	v_exp_f32_e32 v45, v45
	v_add_f32_e32 v213, v213, v42
	s_waitcnt lgkmcnt(6)
	v_mfma_f32_32x32x16_bf16 v[66:81], v[158:161], v[110:113], v[66:81]
	ds_read_b64 v[174:175], v201 offset:4384
	ds_read_b64 v[176:177], v201 offset:4400
	ds_read_b128 v[146:149], v210 offset:0
	ds_read_b128 v[150:153], v210 offset:32
	ds_read_b128 v[154:157], v210 offset:64
	ds_read_b128 v[158:161], v210 offset:96
	v_add_f32_e32 v214, v214, v43
	v_add_f32_e32 v178, v178, v44
	v_add_f32_e32 v179, v179, v45
	v_exp_f32_e32 v46, v46
	v_exp_f32_e32 v47, v47
	v_exp_f32_e32 v48, v48
	s_waitcnt lgkmcnt(10)
	v_mfma_f32_32x32x16_bf16 v[2:17], v[162:165], v[34:37], v[2:17]
	v_exp_f32_e32 v49, v49
	v_add_f32_e32 v213, v213, v46
	v_add_f32_e32 v214, v214, v47
	v_add_f32_e32 v178, v178, v48
	v_add_f32_e32 v179, v179, v49
	v_cvt_pk_bf16_f32 v42, v42, v43
	v_cvt_pk_bf16_f32 v43, v44, v45
	v_cvt_pk_bf16_f32 v44, v46, v47
	s_waitcnt lgkmcnt(8)
	v_mfma_f32_32x32x16_bf16 v[18:33], v[166:169], v[34:37], v[18:33]
	v_cvt_pk_bf16_f32 v45, v48, v49
	s_waitcnt lgkmcnt(0)
	v_add_f32_e32 v66, v66, v146
	v_add_f32_e32 v67, v67, v147
	v_add_f32_e32 v68, v68, v148
	v_add_f32_e32 v69, v69, v149
	v_add_f32_e32 v70, v70, v150
	v_add_f32_e32 v71, v71, v151
	v_add_f32_e32 v72, v72, v152
	v_add_f32_e32 v73, v73, v153
	v_mfma_f32_32x32x16_bf16 v[2:17], v[170:173], v[42:45], v[2:17]
	v_add_f32_e32 v74, v74, v154
	v_add_f32_e32 v75, v75, v155
	v_add_f32_e32 v76, v76, v156
	v_add_f32_e32 v77, v77, v157
	v_add_f32_e32 v78, v78, v158
	v_add_f32_e32 v79, v79, v159
	v_add_f32_e32 v80, v80, v160
	v_add_f32_e32 v81, v81, v161
	v_max3_f32 v216, v66, v67, v68
	v_mfma_f32_32x32x16_bf16 v[18:33], v[174:177], v[42:45], v[18:33]
	s_waitcnt vmcnt(2)
	ds_write_b128 v204, v[188:191] offset:0
	ds_write_b64 v205, v[192:193] offset:8704
	ds_write_b64 v205, v[194:195] offset:8712
	global_load_dwordx4 v[188:191], v206, s[12:13]
	s_add_i32 s20, s20, 1
	s_add_u32 s12, s12, 0x2000
	s_addc_u32 s13, s13, 0
	s_cmp_eq_u32 s20, s22
	s_cselect_b32 s12, s16, s12
	s_cselect_b32 s13, s17, s13
	global_load_dwordx4 v[192:195], v207, s[14:15]
	s_add_i32 s21, s21, 1
	s_add_u32 s14, s14, 0x80
	s_addc_u32 s15, s15, 0
	s_cmp_eq_u32 s21, s22
	s_cselect_b32 s14, s18, s14
	s_cselect_b32 s15, s19, s15
	v_max3_f32 v217, v74, v75, v76
	v_max3_f32 v216, v216, v69, v70
	v_max3_f32 v217, v217, v77, v78
	v_max3_f32 v216, v216, v71, v72
	v_max3_f32 v217, v217, v79, v80
	v_max_f32_e32 v216, v216, v73
	v_max_f32_e32 v217, v217, v81
	v_max_f32_e32 v216, v216, v217
	v_cmp_lt_f32_e32 vcc, 4.0, v216
	s_or_b64 s[28:29], vcc, s[26:27]
	s_cmp_lg_u64 s[28:29], 0
	s_cbranch_scc0 .Lna_nr_w0f
	v_mov_b32_e32 v217, v216
	s_nop 1
	v_permlane32_swap_b32_e32 v216, v217
	v_max_f32_e32 v215, v216, v217
	s_nop 15
	v_max_f32_e32 v216, v215, v220
	v_cmp_lt_f32_e32 vcc, 0xf0c9f2ca, v215
	s_nop 1
	v_cndmask_b32_e32 v216, 0, v216, vcc
	v_exp_f32_e64 v217, -v216
	v_add_f32_e32 v212, v212, v216
	v_and_b32_e32 v217, v217, v221
	v_sub_f32_e32 v66, v66, v216
	v_sub_f32_e32 v67, v67, v216
	v_sub_f32_e32 v68, v68, v216
	v_sub_f32_e32 v69, v69, v216
	v_sub_f32_e32 v70, v70, v216
	v_sub_f32_e32 v71, v71, v216
	v_sub_f32_e32 v72, v72, v216
	v_sub_f32_e32 v73, v73, v216
	v_sub_f32_e32 v74, v74, v216
	v_sub_f32_e32 v75, v75, v216
	v_sub_f32_e32 v76, v76, v216
	v_sub_f32_e32 v77, v77, v216
	v_sub_f32_e32 v78, v78, v216
	v_sub_f32_e32 v79, v79, v216
	v_sub_f32_e32 v80, v80, v216
	v_sub_f32_e32 v81, v81, v216
	v_sub_f32_e32 v114, v114, v216
	v_sub_f32_e32 v115, v115, v216
	v_sub_f32_e32 v116, v116, v216
	v_sub_f32_e32 v117, v117, v216
	v_sub_f32_e32 v118, v118, v216
	v_sub_f32_e32 v119, v119, v216
	v_sub_f32_e32 v120, v120, v216
	v_sub_f32_e32 v121, v121, v216
	v_sub_f32_e32 v122, v122, v216
	v_sub_f32_e32 v123, v123, v216
	v_sub_f32_e32 v124, v124, v216
	v_sub_f32_e32 v125, v125, v216
	v_sub_f32_e32 v126, v126, v216
	v_sub_f32_e32 v127, v127, v216
	v_sub_f32_e32 v128, v128, v216
	v_sub_f32_e32 v129, v129, v216
	v_mul_f32_e32 v213, v213, v217
	v_mul_f32_e32 v214, v214, v217
	v_mul_f32_e32 v178, v178, v217
	v_mul_f32_e32 v179, v179, v217
	v_mul_f32_e32 v2, v2, v217
	v_mul_f32_e32 v3, v3, v217
	v_mul_f32_e32 v4, v4, v217
	v_mul_f32_e32 v5, v5, v217
	v_mul_f32_e32 v6, v6, v217
	v_mul_f32_e32 v7, v7, v217
	v_mul_f32_e32 v8, v8, v217
	v_mul_f32_e32 v9, v9, v217
	v_mul_f32_e32 v10, v10, v217
	v_mul_f32_e32 v11, v11, v217
	v_mul_f32_e32 v12, v12, v217
	v_mul_f32_e32 v13, v13, v217
	v_mul_f32_e32 v14, v14, v217
	v_mul_f32_e32 v15, v15, v217
	v_mul_f32_e32 v16, v16, v217
	v_mul_f32_e32 v17, v17, v217
	v_mul_f32_e32 v18, v18, v217
	v_mul_f32_e32 v19, v19, v217
	v_mul_f32_e32 v20, v20, v217
	v_mul_f32_e32 v21, v21, v217
	v_mul_f32_e32 v22, v22, v217
	v_mul_f32_e32 v23, v23, v217
	v_mul_f32_e32 v24, v24, v217
	v_mul_f32_e32 v25, v25, v217
	v_mul_f32_e32 v26, v26, v217
	v_mul_f32_e32 v27, v27, v217
	v_mul_f32_e32 v28, v28, v217
	v_mul_f32_e32 v29, v29, v217
	v_mul_f32_e32 v30, v30, v217
	v_mul_f32_e32 v31, v31, v217
	v_mul_f32_e32 v32, v32, v217
	v_mul_f32_e32 v33, v33, v217
	v_cndmask_b32_e32 v220, v220, v228, vcc
	v_cndmask_b32_e64 v221, v221, -1, vcc
	s_andn2_b64 s[26:27], s[26:27], vcc

.Lna_slow_w0:
	s_cmp_eq_u64 s[40:41], 0
	s_cbranch_scc1 .Lna_sl_a_w0s
	ds_read_b64 v[162:163], v201 offset:0
	ds_read_b64 v[164:165], v201 offset:16
	ds_read_b64 v[166:167], v201 offset:4352
	ds_read_b64 v[168:169], v201 offset:4368
	ds_read_b64 v[170:171], v201 offset:32
	ds_read_b64 v[172:173], v201 offset:48
	ds_read_b64 v[174:175], v201 offset:4384
	ds_read_b64 v[176:177], v201 offset:4400
	v_exp_f32_e32 v34, v34
	v_exp_f32_e32 v35, v35
	v_exp_f32_e32 v36, v36
	v_exp_f32_e32 v37, v37
	v_add_f32_e32 v213, v213, v34
	v_add_f32_e32 v214, v214, v35
	v_add_f32_e32 v178, v178, v36
	v_add_f32_e32 v179, v179, v37
	v_exp_f32_e32 v38, v38
	v_exp_f32_e32 v39, v39
	v_exp_f32_e32 v40, v40
	v_exp_f32_e32 v41, v41
	v_add_f32_e32 v213, v213, v38
	v_add_f32_e32 v214, v214, v39
	v_add_f32_e32 v178, v178, v40
	v_add_f32_e32 v179, v179, v41
	v_cvt_pk_bf16_f32 v34, v34, v35
	v_cvt_pk_bf16_f32 v35, v36, v37
	v_cvt_pk_bf16_f32 v36, v38, v39
	v_cvt_pk_bf16_f32 v37, v40, v41
	v_exp_f32_e32 v42, v42
	v_exp_f32_e32 v43, v43
	v_exp_f32_e32 v44, v44
	v_exp_f32_e32 v45, v45
	v_add_f32_e32 v213, v213, v42
	v_add_f32_e32 v214, v214, v43
	v_add_f32_e32 v178, v178, v44
	v_add_f32_e32 v179, v179, v45
	v_exp_f32_e32 v46, v46
	v_exp_f32_e32 v47, v47
	v_exp_f32_e32 v48, v48
	v_exp_f32_e32 v49, v49
	v_add_f32_e32 v213, v213, v46
	v_add_f32_e32 v214, v214, v47
	v_add_f32_e32 v178, v178, v48
	v_add_f32_e32 v179, v179, v49
	v_cvt_pk_bf16_f32 v42, v42, v43
	v_cvt_pk_bf16_f32 v43, v44, v45
	v_cvt_pk_bf16_f32 v44, v46, v47
	v_cvt_pk_bf16_f32 v45, v48, v49
	s_nop 1
	s_waitcnt lgkmcnt(6)
	v_mfma_f32_32x32x16_bf16 v[2:17], v[162:165], v[34:37], v[2:17]
	s_waitcnt lgkmcnt(4)
	v_mfma_f32_32x32x16_bf16 v[18:33], v[166:169], v[34:37], v[18:33]
	s_waitcnt lgkmcnt(2)
	v_mfma_f32_32x32x16_bf16 v[2:17], v[170:173], v[42:45], v[2:17]
	s_waitcnt lgkmcnt(0)
	v_mfma_f32_32x32x16_bf16 v[18:33], v[174:177], v[42:45], v[18:33]
.Lna_sl_a_w0s:
	s_waitcnt lgkmcnt(0)
	s_cmp_eq_u64 s[42:43], 0
	s_cbranch_scc1 .Lna_sl_b_w0s
	ds_read_b128 v[146:149], v199 offset:9216
	ds_read_b128 v[150:153], v199 offset:9248
	ds_read_b128 v[154:157], v199 offset:9280
	ds_read_b128 v[158:161], v199 offset:9312
	s_waitcnt lgkmcnt(3)
	v_mfma_f32_32x32x16_bf16 v[66:81], v[146:149], v[98:101], v[114:129]
	s_waitcnt lgkmcnt(2)
	v_mfma_f32_32x32x16_bf16 v[66:81], v[150:153], v[102:105], v[66:81]
	s_waitcnt lgkmcnt(1)
	v_mfma_f32_32x32x16_bf16 v[66:81], v[154:157], v[106:109], v[66:81]
	s_waitcnt lgkmcnt(0)
	v_mfma_f32_32x32x16_bf16 v[66:81], v[158:161], v[110:113], v[66:81]
	v_add_u32_e32 v210, s25, v208
	ds_read_b128 v[146:149], v210 offset:0
	ds_read_b128 v[150:153], v210 offset:32
	ds_read_b128 v[154:157], v210 offset:64
	ds_read_b128 v[158:161], v210 offset:96
	s_waitcnt lgkmcnt(0)
	s_nop 15
	v_add_f32_e32 v66, v66, v146
	v_add_f32_e32 v67, v67, v147
	v_add_f32_e32 v68, v68, v148
	v_add_f32_e32 v69, v69, v149
	v_add_f32_e32 v70, v70, v150
	v_add_f32_e32 v71, v71, v151
	v_add_f32_e32 v72, v72, v152
	v_add_f32_e32 v73, v73, v153
	v_add_f32_e32 v74, v74, v154
	v_add_f32_e32 v75, v75, v155
	v_add_f32_e32 v76, v76, v156
	v_add_f32_e32 v77, v77, v157
	v_add_f32_e32 v78, v78, v158
	v_add_f32_e32 v79, v79, v159
	v_add_f32_e32 v80, v80, v160
	v_add_f32_e32 v81, v81, v161
	v_cndmask_b32_e64 v66, v229, v66, s[48:49]
	v_cndmask_b32_e64 v67, v229, v67, s[48:49]
	v_cndmask_b32_e64 v68, v229, v68, s[48:49]
	v_cndmask_b32_e64 v69, v229, v69, s[48:49]
	v_cndmask_b32_e64 v70, v229, v70, s[48:49]
	v_cndmask_b32_e64 v71, v229, v71, s[48:49]
	v_cndmask_b32_e64 v72, v229, v72, s[48:49]
	v_cndmask_b32_e64 v73, v229, v73, s[48:49]
	v_cndmask_b32_e64 v74, v229, v74, s[48:49]
	v_cndmask_b32_e64 v75, v229, v75, s[48:49]
	v_cndmask_b32_e64 v76, v229, v76, s[48:49]
	v_cndmask_b32_e64 v77, v229, v77, s[48:49]
	v_cndmask_b32_e64 v78, v229, v78, s[48:49]
	v_cndmask_b32_e64 v79, v229, v79, s[48:49]
	v_cndmask_b32_e64 v80, v229, v80, s[48:49]
	v_cndmask_b32_e64 v81, v229, v81, s[48:49]
	v_max3_f32 v216, v66, v67, v68
	v_max3_f32 v217, v74, v75, v76
	v_max3_f32 v216, v216, v69, v70
	v_max3_f32 v217, v217, v77, v78
	v_max3_f32 v216, v216, v71, v72
	v_max3_f32 v217, v217, v79, v80
	v_max_f32_e32 v216, v216, v73
	v_max_f32_e32 v217, v217, v81
	v_max_f32_e32 v216, v216, v217
	v_cmp_lt_f32_e32 vcc, 4.0, v216
	s_or_b64 s[28:29], vcc, s[26:27]
	s_cmp_lg_u64 s[28:29], 0
	s_cbranch_scc0 .Lna_nr_w0s
	v_mov_b32_e32 v217, v216
	s_nop 1
	v_permlane32_swap_b32_e32 v216, v217
	v_max_f32_e32 v215, v216, v217
	s_nop 15
	v_max_f32_e32 v216, v215, v220
	v_cmp_lt_f32_e32 vcc, 0xf0c9f2ca, v215
	s_nop 1
	v_cndmask_b32_e32 v216, 0, v216, vcc
	v_exp_f32_e64 v217, -v216
	v_add_f32_e32 v212, v212, v216
	v_and_b32_e32 v217, v217, v221
	v_sub_f32_e32 v66, v66, v216
	v_sub_f32_e32 v67, v67, v216
	v_sub_f32_e32 v68, v68, v216
	v_sub_f32_e32 v69, v69, v216
	v_sub_f32_e32 v70, v70, v216
	v_sub_f32_e32 v71, v71, v216
	v_sub_f32_e32 v72, v72, v216
	v_sub_f32_e32 v73, v73, v216
	v_sub_f32_e32 v74, v74, v216
	v_sub_f32_e32 v75, v75, v216
	v_sub_f32_e32 v76, v76, v216
	v_sub_f32_e32 v77, v77, v216
	v_sub_f32_e32 v78, v78, v216
	v_sub_f32_e32 v79, v79, v216
	v_sub_f32_e32 v80, v80, v216
	v_sub_f32_e32 v81, v81, v216
	v_sub_f32_e32 v114, v114, v216
	v_sub_f32_e32 v115, v115, v216
	v_sub_f32_e32 v116, v116, v216
	v_sub_f32_e32 v117, v117, v216
	v_sub_f32_e32 v118, v118, v216
	v_sub_f32_e32 v119, v119, v216
	v_sub_f32_e32 v120, v120, v216
	v_sub_f32_e32 v121, v121, v216
	v_sub_f32_e32 v122, v122, v216
	v_sub_f32_e32 v123, v123, v216
	v_sub_f32_e32 v124, v124, v216
	v_sub_f32_e32 v125, v125, v216
	v_sub_f32_e32 v126, v126, v216
	v_sub_f32_e32 v127, v127, v216
	v_sub_f32_e32 v128, v128, v216
	v_sub_f32_e32 v129, v129, v216
	v_mul_f32_e32 v213, v213, v217
	v_mul_f32_e32 v214, v214, v217
	v_mul_f32_e32 v178, v178, v217
	v_mul_f32_e32 v179, v179, v217
	v_mul_f32_e32 v2, v2, v217
	v_mul_f32_e32 v3, v3, v217
	v_mul_f32_e32 v4, v4, v217
	v_mul_f32_e32 v5, v5, v217
	v_mul_f32_e32 v6, v6, v217
	v_mul_f32_e32 v7, v7, v217
	v_mul_f32_e32 v8, v8, v217
	v_mul_f32_e32 v9, v9, v217
	v_mul_f32_e32 v10, v10, v217
	v_mul_f32_e32 v11, v11, v217
	v_mul_f32_e32 v12, v12, v217
	v_mul_f32_e32 v13, v13, v217
	v_mul_f32_e32 v14, v14, v217
	v_mul_f32_e32 v15, v15, v217
	v_mul_f32_e32 v16, v16, v217
	v_mul_f32_e32 v17, v17, v217
	v_mul_f32_e32 v18, v18, v217
	v_mul_f32_e32 v19, v19, v217
	v_mul_f32_e32 v20, v20, v217
	v_mul_f32_e32 v21, v21, v217
	v_mul_f32_e32 v22, v22, v217
	v_mul_f32_e32 v23, v23, v217
	v_mul_f32_e32 v24, v24, v217
	v_mul_f32_e32 v25, v25, v217
	v_mul_f32_e32 v26, v26, v217
	v_mul_f32_e32 v27, v27, v217
	v_mul_f32_e32 v28, v28, v217
	v_mul_f32_e32 v29, v29, v217
	v_mul_f32_e32 v30, v30, v217
	v_mul_f32_e32 v31, v31, v217
	v_mul_f32_e32 v32, v32, v217
	v_mul_f32_e32 v33, v33, v217
	v_cndmask_b32_e32 v220, v220, v228, vcc
	v_cndmask_b32_e64 v221, v221, -1, vcc
	s_andn2_b64 s[26:27], s[26:27], vcc

.Lna_done_w0:
	s_add_i32 s24, s24, 1
	s_add_i32 s25, s25, 0x150
	s_add_i32 s33, s33, -1
	s_cmp_lg_u32 s33, 0
	s_cbranch_scc1 .Lna_wloop
	v_sub_f32_e32 v114, 0, v212
	v_mov_b32_e32 v115, v114
	v_mov_b32_e32 v116, v114
	v_mov_b32_e32 v117, v114
	v_mov_b32_e32 v118, v114
	v_mov_b32_e32 v119, v114
	v_mov_b32_e32 v120, v114
	v_mov_b32_e32 v121, v114
	v_mov_b32_e32 v122, v114
	v_mov_b32_e32 v123, v114
	v_mov_b32_e32 v124, v114
	v_mov_b32_e32 v125, v114
	v_mov_b32_e32 v126, v114
	v_mov_b32_e32 v127, v114
	v_mov_b32_e32 v128, v114
	v_mov_b32_e32 v129, v114
	v_mov_b32_e32 v130, v114
	v_mov_b32_e32 v131, v114
	v_mov_b32_e32 v132, v114
	v_mov_b32_e32 v133, v114
	v_mov_b32_e32 v134, v114
	v_mov_b32_e32 v135, v114
	v_mov_b32_e32 v136, v114
	v_mov_b32_e32 v137, v114
	v_mov_b32_e32 v138, v114
	v_mov_b32_e32 v139, v114
	v_mov_b32_e32 v140, v114
	v_mov_b32_e32 v141, v114
	v_mov_b32_e32 v142, v114
	v_mov_b32_e32 v143, v114
	v_mov_b32_e32 v144, v114
	v_mov_b32_e32 v145, v114
	s_sub_i32 s36, s24, s23
	s_cmp_lt_u32 s36, s63
	s_cselect_b64 s[40:41], -1, 0
	s_mov_b64 s[42:43], -1
	s_cmp_eq_u64 s[40:41], 0
	s_cbranch_scc1 .Lna_slow_wc
	ds_read_b128 v[146:149], v200 offset:0
	ds_read_b128 v[150:153], v200 offset:4608
	ds_read_b128 v[154:157], v200 offset:32
	ds_read_b128 v[158:161], v200 offset:4640
	v_exp_f32_e32 v66, v66
	v_exp_f32_e32 v67, v67
	v_exp_f32_e32 v68, v68
	s_waitcnt lgkmcnt(2)
	v_mfma_f32_32x32x16_bf16 v[34:49], v[146:149], v[98:101], v[114:129]
	ds_read_b128 v[146:149], v200 offset:64
	v_exp_f32_e32 v69, v69
	v_add_f32_e32 v213, v213, v66
	v_add_f32_e32 v214, v214, v67
	v_add_f32_e32 v178, v178, v68
	v_add_f32_e32 v179, v179, v69
	v_mfma_f32_32x32x16_bf16 v[50:65], v[150:153], v[98:101], v[130:145]
	ds_read_b128 v[150:153], v200 offset:4672
	v_exp_f32_e32 v70, v70
	v_exp_f32_e32 v71, v71
	v_exp_f32_e32 v72, v72
	s_waitcnt lgkmcnt(2)
	v_mfma_f32_32x32x16_bf16 v[34:49], v[154:157], v[102:105], v[34:49]
	ds_read_b128 v[154:157], v200 offset:96
	v_exp_f32_e32 v73, v73
	v_add_f32_e32 v213, v213, v70
	v_add_f32_e32 v214, v214, v71
	v_add_f32_e32 v178, v178, v72
	v_mfma_f32_32x32x16_bf16 v[50:65], v[158:161], v[102:105], v[50:65]
	ds_read_b128 v[158:161], v200 offset:4704
	v_add_f32_e32 v179, v179, v73
	v_cvt_pk_bf16_f32 v66, v66, v67
	v_cvt_pk_bf16_f32 v67, v68, v69
	v_cvt_pk_bf16_f32 v68, v70, v71
	v_cvt_pk_bf16_f32 v69, v72, v73
	v_exp_f32_e32 v74, v74
	s_waitcnt lgkmcnt(2)
	v_mfma_f32_32x32x16_bf16 v[34:49], v[146:149], v[106:109], v[34:49]
	ds_read_b64 v[162:163], v201 offset:8704
	ds_read_b64 v[164:165], v201 offset:8720
	v_exp_f32_e32 v75, v75
	v_exp_f32_e32 v76, v76
	v_exp_f32_e32 v77, v77
	v_mfma_f32_32x32x16_bf16 v[50:65], v[150:153], v[106:109], v[50:65]
	ds_read_b64 v[166:167], v201 offset:13056
	ds_read_b64 v[168:169], v201 offset:13072
	v_add_f32_e32 v213, v213, v74
	v_add_f32_e32 v214, v214, v75
	v_add_f32_e32 v178, v178, v76
	v_add_f32_e32 v179, v179, v77
	s_waitcnt lgkmcnt(4)
	v_mfma_f32_32x32x16_bf16 v[34:49], v[154:157], v[110:113], v[34:49]
	ds_read_b64 v[170:171], v201 offset:8736
	ds_read_b64 v[172:173], v201 offset:8752
	v_exp_f32_e32 v78, v78
	v_exp_f32_e32 v79, v79
	v_exp_f32_e32 v80, v80
	v_mfma_f32_32x32x16_bf16 v[50:65], v[158:161], v[110:113], v[50:65]
	ds_read_b64 v[174:175], v201 offset:13088
	ds_read_b64 v[176:177], v201 offset:13104
	v_exp_f32_e32 v81, v81
	v_add_f32_e32 v213, v213, v78
	v_add_f32_e32 v214, v214, v79
	v_add_f32_e32 v178, v178, v80
	v_add_f32_e32 v179, v179, v81
	s_waitcnt lgkmcnt(6)
	v_mfma_f32_32x32x16_bf16 v[2:17], v[162:165], v[66:69], v[2:17]
	v_cvt_pk_bf16_f32 v74, v74, v75
	v_cvt_pk_bf16_f32 v75, v76, v77
	v_cvt_pk_bf16_f32 v76, v78, v79
	v_cvt_pk_bf16_f32 v77, v80, v81
	s_waitcnt lgkmcnt(4)
	v_mfma_f32_32x32x16_bf16 v[18:33], v[166:169], v[66:69], v[18:33]
	v_max3_f32 v216, v34, v35, v36
	v_max3_f32 v217, v50, v51, v52
	v_max3_f32 v216, v216, v37, v38
	v_max3_f32 v217, v217, v53, v54
	v_max3_f32 v216, v216, v39, v40
	v_max3_f32 v217, v217, v55, v56
	v_max3_f32 v216, v216, v41, v42
	s_waitcnt lgkmcnt(2)
	v_mfma_f32_32x32x16_bf16 v[2:17], v[170:173], v[74:77], v[2:17]
	v_max3_f32 v217, v217, v57, v58
	v_max3_f32 v216, v216, v43, v44
	v_max3_f32 v217, v217, v59, v60
	v_max3_f32 v216, v216, v45, v46
	v_max3_f32 v217, v217, v61, v62
	v_max3_f32 v216, v216, v47, v48
	s_waitcnt lgkmcnt(0)
	v_mfma_f32_32x32x16_bf16 v[18:33], v[174:177], v[74:77], v[18:33]
	s_waitcnt vmcnt(2)
	ds_write_b128 v204, v[230:233] offset:9216
	ds_write_b64 v205, v[234:235] offset:0
	ds_write_b64 v205, v[236:237] offset:8
	global_load_dwordx4 v[230:233], v206, s[12:13]
	s_add_u32 s12, s12, 0x2000
	s_addc_u32 s13, s13, 0
	global_load_dwordx4 v[234:237], v207, s[14:15]
	s_add_u32 s14, s14, 0x80
	s_addc_u32 s15, s15, 0
	v_max3_f32 v217, v217, v63, v64
	v_max_f32_e32 v216, v216, v49
	v_max_f32_e32 v217, v217, v65
	v_max_f32_e32 v216, v216, v217
	v_cmp_lt_f32_e32 vcc, 4.0, v216
	s_cbranch_vccz .Lna_nr_wcf
	v_mov_b32_e32 v217, v216
	s_nop 1
	v_permlane32_swap_b32_e32 v216, v217
	v_max_f32_e32 v215, v216, v217
	s_nop 15
	v_max_f32_e32 v216, v215, v220
	v_exp_f32_e64 v217, -v216
	v_add_f32_e32 v212, v212, v216
	v_and_b32_e32 v217, v217, v221
	v_sub_f32_e32 v34, v34, v216
	v_sub_f32_e32 v35, v35, v216
	v_sub_f32_e32 v36, v36, v216
	v_sub_f32_e32 v37, v37, v216
	v_sub_f32_e32 v38, v38, v216
	v_sub_f32_e32 v39, v39, v216
	v_sub_f32_e32 v40, v40, v216
	v_sub_f32_e32 v41, v41, v216
	v_sub_f32_e32 v42, v42, v216
	v_sub_f32_e32 v43, v43, v216
	v_sub_f32_e32 v44, v44, v216
	v_sub_f32_e32 v45, v45, v216
	v_sub_f32_e32 v46, v46, v216
	v_sub_f32_e32 v47, v47, v216
	v_sub_f32_e32 v48, v48, v216
	v_sub_f32_e32 v49, v49, v216
	v_sub_f32_e32 v50, v50, v216
	v_sub_f32_e32 v51, v51, v216
	v_sub_f32_e32 v52, v52, v216
	v_sub_f32_e32 v53, v53, v216
	v_sub_f32_e32 v54, v54, v216
	v_sub_f32_e32 v55, v55, v216
	v_sub_f32_e32 v56, v56, v216
	v_sub_f32_e32 v57, v57, v216
	v_sub_f32_e32 v58, v58, v216
	v_sub_f32_e32 v59, v59, v216
	v_sub_f32_e32 v60, v60, v216
	v_sub_f32_e32 v61, v61, v216
	v_sub_f32_e32 v62, v62, v216
	v_sub_f32_e32 v63, v63, v216
	v_sub_f32_e32 v64, v64, v216
	v_sub_f32_e32 v65, v65, v216
	v_sub_f32_e32 v114, v114, v216
	v_sub_f32_e32 v115, v115, v216
	v_sub_f32_e32 v116, v116, v216
	v_sub_f32_e32 v117, v117, v216
	v_sub_f32_e32 v118, v118, v216
	v_sub_f32_e32 v119, v119, v216
	v_sub_f32_e32 v120, v120, v216
	v_sub_f32_e32 v121, v121, v216
	v_sub_f32_e32 v122, v122, v216
	v_sub_f32_e32 v123, v123, v216
	v_sub_f32_e32 v124, v124, v216
	v_sub_f32_e32 v125, v125, v216
	v_sub_f32_e32 v126, v126, v216
	v_sub_f32_e32 v127, v127, v216
	v_sub_f32_e32 v128, v128, v216
	v_sub_f32_e32 v129, v129, v216
	v_sub_f32_e32 v130, v130, v216
	v_sub_f32_e32 v131, v131, v216
	v_sub_f32_e32 v132, v132, v216
	v_sub_f32_e32 v133, v133, v216
	v_sub_f32_e32 v134, v134, v216
	v_sub_f32_e32 v135, v135, v216
	v_sub_f32_e32 v136, v136, v216
	v_sub_f32_e32 v137, v137, v216
	v_sub_f32_e32 v138, v138, v216
	v_sub_f32_e32 v139, v139, v216
	v_sub_f32_e32 v140, v140, v216
	v_sub_f32_e32 v141, v141, v216
	v_sub_f32_e32 v142, v142, v216
	v_sub_f32_e32 v143, v143, v216
	v_sub_f32_e32 v144, v144, v216
	v_sub_f32_e32 v145, v145, v216
	v_mul_f32_e32 v213, v213, v217
	v_mul_f32_e32 v214, v214, v217
	v_mul_f32_e32 v178, v178, v217
	v_mul_f32_e32 v179, v179, v217
	v_mul_f32_e32 v2, v2, v217
	v_mul_f32_e32 v3, v3, v217
	v_mul_f32_e32 v4, v4, v217
	v_mul_f32_e32 v5, v5, v217
	v_mul_f32_e32 v6, v6, v217
	v_mul_f32_e32 v7, v7, v217
	v_mul_f32_e32 v8, v8, v217
	v_mul_f32_e32 v9, v9, v217
	v_mul_f32_e32 v10, v10, v217
	v_mul_f32_e32 v11, v11, v217
	v_mul_f32_e32 v12, v12, v217
	v_mul_f32_e32 v13, v13, v217
	v_mul_f32_e32 v14, v14, v217
	v_mul_f32_e32 v15, v15, v217
	v_mul_f32_e32 v16, v16, v217
	v_mul_f32_e32 v17, v17, v217
	v_mul_f32_e32 v18, v18, v217
	v_mul_f32_e32 v19, v19, v217
	v_mul_f32_e32 v20, v20, v217
	v_mul_f32_e32 v21, v21, v217
	v_mul_f32_e32 v22, v22, v217
	v_mul_f32_e32 v23, v23, v217
	v_mul_f32_e32 v24, v24, v217
	v_mul_f32_e32 v25, v25, v217
	v_mul_f32_e32 v26, v26, v217
	v_mul_f32_e32 v27, v27, v217
	v_mul_f32_e32 v28, v28, v217
	v_mul_f32_e32 v29, v29, v217
	v_mul_f32_e32 v30, v30, v217
	v_mul_f32_e32 v31, v31, v217
	v_mul_f32_e32 v32, v32, v217
	v_mul_f32_e32 v33, v33, v217

.Lna_sl_a_wcs:
	s_waitcnt lgkmcnt(0)
	s_cmp_eq_u64 s[42:43], 0
	s_cbranch_scc1 .Lna_sl_b_wcs
	ds_read_b128 v[146:149], v200 offset:0
	ds_read_b128 v[150:153], v200 offset:4608
	ds_read_b128 v[154:157], v200 offset:32
	ds_read_b128 v[158:161], v200 offset:4640
	ds_read_b128 v[162:165], v200 offset:64
	ds_read_b128 v[166:169], v200 offset:4672
	ds_read_b128 v[170:173], v200 offset:96
	ds_read_b128 v[174:177], v200 offset:4704
	s_waitcnt lgkmcnt(7)
	v_mfma_f32_32x32x16_bf16 v[34:49], v[146:149], v[98:101], v[114:129]
	s_waitcnt lgkmcnt(6)
	v_mfma_f32_32x32x16_bf16 v[50:65], v[150:153], v[98:101], v[130:145]
	s_waitcnt lgkmcnt(5)
	v_mfma_f32_32x32x16_bf16 v[34:49], v[154:157], v[102:105], v[34:49]
	s_waitcnt lgkmcnt(4)
	v_mfma_f32_32x32x16_bf16 v[50:65], v[158:161], v[102:105], v[50:65]
	s_waitcnt lgkmcnt(3)
	v_mfma_f32_32x32x16_bf16 v[34:49], v[162:165], v[106:109], v[34:49]
	s_waitcnt lgkmcnt(2)
	v_mfma_f32_32x32x16_bf16 v[50:65], v[166:169], v[106:109], v[50:65]
	s_waitcnt lgkmcnt(1)
	v_mfma_f32_32x32x16_bf16 v[34:49], v[170:173], v[110:113], v[34:49]
	s_waitcnt lgkmcnt(0)
	v_mfma_f32_32x32x16_bf16 v[50:65], v[174:177], v[110:113], v[50:65]
	s_nop 15
	v_max3_f32 v216, v34, v35, v36
	v_max3_f32 v217, v50, v51, v52
	v_max3_f32 v216, v216, v37, v38
	v_max3_f32 v217, v217, v53, v54
	v_max3_f32 v216, v216, v39, v40
	v_max3_f32 v217, v217, v55, v56
	v_max3_f32 v216, v216, v41, v42
	v_max3_f32 v217, v217, v57, v58
	v_max3_f32 v216, v216, v43, v44
	v_max3_f32 v217, v217, v59, v60
	v_max3_f32 v216, v216, v45, v46
	v_max3_f32 v217, v217, v61, v62
	v_max3_f32 v216, v216, v47, v48
	v_max3_f32 v217, v217, v63, v64
	v_max_f32_e32 v216, v216, v49
	v_max_f32_e32 v217, v217, v65
	v_max_f32_e32 v216, v216, v217
	v_cmp_lt_f32_e32 vcc, 4.0, v216
	s_cbranch_vccz .Lna_nr_wcs
	v_mov_b32_e32 v217, v216
	s_nop 1
	v_permlane32_swap_b32_e32 v216, v217
	v_max_f32_e32 v215, v216, v217
	s_nop 15
	v_max_f32_e32 v216, v215, v220
	v_exp_f32_e64 v217, -v216
	v_add_f32_e32 v212, v212, v216
	v_and_b32_e32 v217, v217, v221
	v_sub_f32_e32 v34, v34, v216
	v_sub_f32_e32 v35, v35, v216
	v_sub_f32_e32 v36, v36, v216
	v_sub_f32_e32 v37, v37, v216
	v_sub_f32_e32 v38, v38, v216
	v_sub_f32_e32 v39, v39, v216
	v_sub_f32_e32 v40, v40, v216
	v_sub_f32_e32 v41, v41, v216
	v_sub_f32_e32 v42, v42, v216
	v_sub_f32_e32 v43, v43, v216
	v_sub_f32_e32 v44, v44, v216
	v_sub_f32_e32 v45, v45, v216
	v_sub_f32_e32 v46, v46, v216
	v_sub_f32_e32 v47, v47, v216
	v_sub_f32_e32 v48, v48, v216
	v_sub_f32_e32 v49, v49, v216
	v_sub_f32_e32 v50, v50, v216
	v_sub_f32_e32 v51, v51, v216
	v_sub_f32_e32 v52, v52, v216
	v_sub_f32_e32 v53, v53, v216
	v_sub_f32_e32 v54, v54, v216
	v_sub_f32_e32 v55, v55, v216
	v_sub_f32_e32 v56, v56, v216
	v_sub_f32_e32 v57, v57, v216
	v_sub_f32_e32 v58, v58, v216
	v_sub_f32_e32 v59, v59, v216
	v_sub_f32_e32 v60, v60, v216
	v_sub_f32_e32 v61, v61, v216
	v_sub_f32_e32 v62, v62, v216
	v_sub_f32_e32 v63, v63, v216
	v_sub_f32_e32 v64, v64, v216
	v_sub_f32_e32 v65, v65, v216
	v_sub_f32_e32 v114, v114, v216
	v_sub_f32_e32 v115, v115, v216
	v_sub_f32_e32 v116, v116, v216
	v_sub_f32_e32 v117, v117, v216
	v_sub_f32_e32 v118, v118, v216
	v_sub_f32_e32 v119, v119, v216
	v_sub_f32_e32 v120, v120, v216
	v_sub_f32_e32 v121, v121, v216
	v_sub_f32_e32 v122, v122, v216
	v_sub_f32_e32 v123, v123, v216
	v_sub_f32_e32 v124, v124, v216
	v_sub_f32_e32 v125, v125, v216
	v_sub_f32_e32 v126, v126, v216
	v_sub_f32_e32 v127, v127, v216
	v_sub_f32_e32 v128, v128, v216
	v_sub_f32_e32 v129, v129, v216
	v_sub_f32_e32 v130, v130, v216
	v_sub_f32_e32 v131, v131, v216
	v_sub_f32_e32 v132, v132, v216
	v_sub_f32_e32 v133, v133, v216
	v_sub_f32_e32 v134, v134, v216
	v_sub_f32_e32 v135, v135, v216
	v_sub_f32_e32 v136, v136, v216
	v_sub_f32_e32 v137, v137, v216
	v_sub_f32_e32 v138, v138, v216
	v_sub_f32_e32 v139, v139, v216
	v_sub_f32_e32 v140, v140, v216
	v_sub_f32_e32 v141, v141, v216
	v_sub_f32_e32 v142, v142, v216
	v_sub_f32_e32 v143, v143, v216
	v_sub_f32_e32 v144, v144, v216
	v_sub_f32_e32 v145, v145, v216
	v_mul_f32_e32 v213, v213, v217
	v_mul_f32_e32 v214, v214, v217
	v_mul_f32_e32 v178, v178, v217
	v_mul_f32_e32 v179, v179, v217
	v_mul_f32_e32 v2, v2, v217
	v_mul_f32_e32 v3, v3, v217
	v_mul_f32_e32 v4, v4, v217
	v_mul_f32_e32 v5, v5, v217
	v_mul_f32_e32 v6, v6, v217
	v_mul_f32_e32 v7, v7, v217
	v_mul_f32_e32 v8, v8, v217
	v_mul_f32_e32 v9, v9, v217
	v_mul_f32_e32 v10, v10, v217
	v_mul_f32_e32 v11, v11, v217
	v_mul_f32_e32 v12, v12, v217
	v_mul_f32_e32 v13, v13, v217
	v_mul_f32_e32 v14, v14, v217
	v_mul_f32_e32 v15, v15, v217
	v_mul_f32_e32 v16, v16, v217
	v_mul_f32_e32 v17, v17, v217
	v_mul_f32_e32 v18, v18, v217
	v_mul_f32_e32 v19, v19, v217
	v_mul_f32_e32 v20, v20, v217
	v_mul_f32_e32 v21, v21, v217
	v_mul_f32_e32 v22, v22, v217
	v_mul_f32_e32 v23, v23, v217
	v_mul_f32_e32 v24, v24, v217
	v_mul_f32_e32 v25, v25, v217
	v_mul_f32_e32 v26, v26, v217
	v_mul_f32_e32 v27, v27, v217
	v_mul_f32_e32 v28, v28, v217
	v_mul_f32_e32 v29, v29, v217
	v_mul_f32_e32 v30, v30, v217
	v_mul_f32_e32 v31, v31, v217
	v_mul_f32_e32 v32, v32, v217
	v_mul_f32_e32 v33, v33, v217

.Lna_done_wc:
	ds_read_b128 v[146:149], v200 offset:9216
	ds_read_b128 v[150:153], v200 offset:13824
	ds_read_b128 v[154:157], v200 offset:9248
	ds_read_b128 v[158:161], v200 offset:13856
	v_exp_f32_e32 v34, v34
	v_exp_f32_e32 v35, v35
	v_exp_f32_e32 v36, v36
	v_exp_f32_e32 v37, v37
	s_waitcnt lgkmcnt(2)
	v_mfma_f32_32x32x16_bf16 v[66:81], v[146:149], v[98:101], v[114:129]
	ds_read_b128 v[146:149], v200 offset:9280
	v_add_f32_e32 v213, v213, v34
	v_add_f32_e32 v214, v214, v35
	v_add_f32_e32 v178, v178, v36
	v_add_f32_e32 v179, v179, v37
	v_exp_f32_e32 v38, v38
	v_exp_f32_e32 v39, v39
	v_mfma_f32_32x32x16_bf16 v[82:97], v[150:153], v[98:101], v[130:145]
	ds_read_b128 v[150:153], v200 offset:13888
	v_exp_f32_e32 v40, v40
	v_exp_f32_e32 v41, v41
	v_add_f32_e32 v213, v213, v38
	v_add_f32_e32 v214, v214, v39
	v_add_f32_e32 v178, v178, v40
	s_waitcnt lgkmcnt(2)
	v_mfma_f32_32x32x16_bf16 v[66:81], v[154:157], v[102:105], v[66:81]
	ds_read_b128 v[154:157], v200 offset:9312
	v_add_f32_e32 v179, v179, v41
	v_cvt_pk_bf16_f32 v34, v34, v35
	v_cvt_pk_bf16_f32 v35, v36, v37
	v_cvt_pk_bf16_f32 v36, v38, v39
	v_cvt_pk_bf16_f32 v37, v40, v41
	v_exp_f32_e32 v42, v42
	v_exp_f32_e32 v43, v43
	v_mfma_f32_32x32x16_bf16 v[82:97], v[158:161], v[102:105], v[82:97]
	ds_read_b128 v[158:161], v200 offset:13920
	v_exp_f32_e32 v44, v44
	v_exp_f32_e32 v45, v45
	v_add_f32_e32 v213, v213, v42
	v_add_f32_e32 v214, v214, v43
	v_add_f32_e32 v178, v178, v44
	s_waitcnt lgkmcnt(2)
	v_mfma_f32_32x32x16_bf16 v[66:81], v[146:149], v[106:109], v[66:81]
	ds_read_b64 v[162:163], v202 offset:0
	ds_read_b64 v[164:165], v202 offset:16
	v_add_f32_e32 v179, v179, v45
	v_exp_f32_e32 v46, v46
	v_exp_f32_e32 v47, v47
	v_exp_f32_e32 v48, v48
	v_mfma_f32_32x32x16_bf16 v[82:97], v[150:153], v[106:109], v[82:97]
	ds_read_b64 v[166:167], v202 offset:4352
	ds_read_b64 v[168:169], v202 offset:4368
	v_exp_f32_e32 v49, v49
	v_add_f32_e32 v213, v213, v46
	v_add_f32_e32 v214, v214, v47
	v_add_f32_e32 v178, v178, v48
	v_add_f32_e32 v179, v179, v49
	v_cvt_pk_bf16_f32 v42, v42, v43
	v_cvt_pk_bf16_f32 v43, v44, v45
	s_waitcnt lgkmcnt(4)
	v_mfma_f32_32x32x16_bf16 v[66:81], v[154:157], v[110:113], v[66:81]
	ds_read_b64 v[170:171], v202 offset:32
	ds_read_b64 v[172:173], v202 offset:48
	v_cvt_pk_bf16_f32 v44, v46, v47
	v_cvt_pk_bf16_f32 v45, v48, v49
	v_exp_f32_e32 v50, v50
	v_exp_f32_e32 v51, v51
	v_exp_f32_e32 v52, v52
	v_mfma_f32_32x32x16_bf16 v[82:97], v[158:161], v[110:113], v[82:97]
	ds_read_b64 v[174:175], v202 offset:4384
	ds_read_b64 v[176:177], v202 offset:4400
	v_exp_f32_e32 v53, v53
	v_add_f32_e32 v213, v213, v50
	v_add_f32_e32 v214, v214, v51
	v_add_f32_e32 v178, v178, v52
	v_add_f32_e32 v179, v179, v53
	v_exp_f32_e32 v54, v54
	s_waitcnt lgkmcnt(6)
	v_mfma_f32_32x32x16_bf16 v[2:17], v[162:165], v[34:37], v[2:17]
	ds_read_b64 v[162:163], v202 offset:64
	ds_read_b64 v[164:165], v202 offset:80
	v_exp_f32_e32 v55, v55
	v_exp_f32_e32 v56, v56
	v_exp_f32_e32 v57, v57
	v_add_f32_e32 v213, v213, v54
	s_waitcnt lgkmcnt(6)
	v_mfma_f32_32x32x16_bf16 v[18:33], v[166:169], v[34:37], v[18:33]
	ds_read_b64 v[166:167], v202 offset:4416
	ds_read_b64 v[168:169], v202 offset:4432
	v_add_f32_e32 v214, v214, v55
	v_add_f32_e32 v178, v178, v56
	v_add_f32_e32 v179, v179, v57
	v_cvt_pk_bf16_f32 v50, v50, v51
	v_cvt_pk_bf16_f32 v51, v52, v53
	v_cvt_pk_bf16_f32 v52, v54, v55
	v_cvt_pk_bf16_f32 v53, v56, v57
	v_exp_f32_e32 v58, v58
	s_waitcnt lgkmcnt(6)
	v_mfma_f32_32x32x16_bf16 v[2:17], v[170:173], v[42:45], v[2:17]
	ds_read_b64 v[170:171], v202 offset:96
	ds_read_b64 v[172:173], v202 offset:112
	v_exp_f32_e32 v59, v59
	v_exp_f32_e32 v60, v60
	v_exp_f32_e32 v61, v61
	s_waitcnt lgkmcnt(6)
	v_mfma_f32_32x32x16_bf16 v[18:33], v[174:177], v[42:45], v[18:33]
	ds_read_b64 v[174:175], v202 offset:4448
	ds_read_b64 v[176:177], v202 offset:4464
	s_waitcnt vmcnt(2)
	ds_write_b128 v204, v[188:191] offset:0
	ds_write_b64 v205, v[192:193] offset:8704
	ds_write_b64 v205, v[194:195] offset:8712
	global_load_dwordx4 v[192:195], v207, s[14:15]
	s_add_u32 s14, s14, 0x80
	s_addc_u32 s15, s15, 0
	v_add_f32_e32 v213, v213, v58
	v_add_f32_e32 v214, v214, v59
	v_add_f32_e32 v178, v178, v60
	v_add_f32_e32 v179, v179, v61
	v_exp_f32_e32 v62, v62
	v_exp_f32_e32 v63, v63
	s_waitcnt lgkmcnt(9)
	v_mfma_f32_32x32x16_bf16 v[2:17], v[162:165], v[50:53], v[2:17]
	v_exp_f32_e32 v64, v64
	v_exp_f32_e32 v65, v65
	v_add_f32_e32 v213, v213, v62
	v_add_f32_e32 v214, v214, v63
	v_add_f32_e32 v178, v178, v64
	v_add_f32_e32 v179, v179, v65
	s_waitcnt lgkmcnt(7)
	v_mfma_f32_32x32x16_bf16 v[18:33], v[166:169], v[50:53], v[18:33]
	v_cvt_pk_bf16_f32 v58, v58, v59
	v_cvt_pk_bf16_f32 v59, v60, v61
	v_cvt_pk_bf16_f32 v60, v62, v63
	v_cvt_pk_bf16_f32 v61, v64, v65
	v_max3_f32 v216, v66, v67, v68
	v_max3_f32 v217, v82, v83, v84
	v_max3_f32 v216, v216, v69, v70
	s_waitcnt lgkmcnt(5)
	v_mfma_f32_32x32x16_bf16 v[2:17], v[170:173], v[58:61], v[2:17]
	v_max3_f32 v217, v217, v85, v86
	v_max3_f32 v216, v216, v71, v72
	v_max3_f32 v217, v217, v87, v88
	v_max3_f32 v216, v216, v73, v74
	v_max3_f32 v217, v217, v89, v90
	v_max3_f32 v216, v216, v75, v76
	v_max3_f32 v217, v217, v91, v92
	v_max3_f32 v216, v216, v77, v78
	s_waitcnt lgkmcnt(3)
	v_mfma_f32_32x32x16_bf16 v[18:33], v[174:177], v[58:61], v[18:33]
	v_max3_f32 v217, v217, v93, v94
	v_max3_f32 v216, v216, v79, v80
	v_max3_f32 v217, v217, v95, v96
	v_max_f32_e32 v216, v216, v81
	v_max_f32_e32 v217, v217, v97
	v_max_f32_e32 v216, v216, v217
	v_cmp_lt_f32_e32 vcc, 4.0, v216
	s_cbranch_vccz .Lna_nr_c0
	v_mov_b32_e32 v217, v216
	s_nop 1
	v_permlane32_swap_b32_e32 v216, v217
	v_max_f32_e32 v215, v216, v217
	s_nop 15
	v_max_f32_e32 v216, v215, v220
	v_exp_f32_e64 v217, -v216
	v_add_f32_e32 v212, v212, v216
	v_and_b32_e32 v217, v217, v221
	v_sub_f32_e32 v66, v66, v216
	v_sub_f32_e32 v67, v67, v216
	v_sub_f32_e32 v68, v68, v216
	v_sub_f32_e32 v69, v69, v216
	v_sub_f32_e32 v70, v70, v216
	v_sub_f32_e32 v71, v71, v216
	v_sub_f32_e32 v72, v72, v216
	v_sub_f32_e32 v73, v73, v216
	v_sub_f32_e32 v74, v74, v216
	v_sub_f32_e32 v75, v75, v216
	v_sub_f32_e32 v76, v76, v216
	v_sub_f32_e32 v77, v77, v216
	v_sub_f32_e32 v78, v78, v216
	v_sub_f32_e32 v79, v79, v216
	v_sub_f32_e32 v80, v80, v216
	v_sub_f32_e32 v81, v81, v216
	v_sub_f32_e32 v82, v82, v216
	v_sub_f32_e32 v83, v83, v216
	v_sub_f32_e32 v84, v84, v216
	v_sub_f32_e32 v85, v85, v216
	v_sub_f32_e32 v86, v86, v216
	v_sub_f32_e32 v87, v87, v216
	v_sub_f32_e32 v88, v88, v216
	v_sub_f32_e32 v89, v89, v216
	v_sub_f32_e32 v90, v90, v216
	v_sub_f32_e32 v91, v91, v216
	v_sub_f32_e32 v92, v92, v216
	v_sub_f32_e32 v93, v93, v216
	v_sub_f32_e32 v94, v94, v216
	v_sub_f32_e32 v95, v95, v216
	v_sub_f32_e32 v96, v96, v216
	v_sub_f32_e32 v97, v97, v216
	v_sub_f32_e32 v114, v114, v216
	v_sub_f32_e32 v115, v115, v216
	v_sub_f32_e32 v116, v116, v216
	v_sub_f32_e32 v117, v117, v216
	v_sub_f32_e32 v118, v118, v216
	v_sub_f32_e32 v119, v119, v216
	v_sub_f32_e32 v120, v120, v216
	v_sub_f32_e32 v121, v121, v216
	v_sub_f32_e32 v122, v122, v216
	v_sub_f32_e32 v123, v123, v216
	v_sub_f32_e32 v124, v124, v216
	v_sub_f32_e32 v125, v125, v216
	v_sub_f32_e32 v126, v126, v216
	v_sub_f32_e32 v127, v127, v216
	v_sub_f32_e32 v128, v128, v216
	v_sub_f32_e32 v129, v129, v216
	v_sub_f32_e32 v130, v130, v216
	v_sub_f32_e32 v131, v131, v216
	v_sub_f32_e32 v132, v132, v216
	v_sub_f32_e32 v133, v133, v216
	v_sub_f32_e32 v134, v134, v216
	v_sub_f32_e32 v135, v135, v216
	v_sub_f32_e32 v136, v136, v216
	v_sub_f32_e32 v137, v137, v216
	v_sub_f32_e32 v138, v138, v216
	v_sub_f32_e32 v139, v139, v216
	v_sub_f32_e32 v140, v140, v216
	v_sub_f32_e32 v141, v141, v216
	v_sub_f32_e32 v142, v142, v216
	v_sub_f32_e32 v143, v143, v216
	v_sub_f32_e32 v144, v144, v216
	v_sub_f32_e32 v145, v145, v216
	v_mul_f32_e32 v213, v213, v217
	v_mul_f32_e32 v214, v214, v217
	v_mul_f32_e32 v178, v178, v217
	v_mul_f32_e32 v179, v179, v217
	v_mul_f32_e32 v2, v2, v217
	v_mul_f32_e32 v3, v3, v217
	v_mul_f32_e32 v4, v4, v217
	v_mul_f32_e32 v5, v5, v217
	v_mul_f32_e32 v6, v6, v217
	v_mul_f32_e32 v7, v7, v217
	v_mul_f32_e32 v8, v8, v217
	v_mul_f32_e32 v9, v9, v217
	v_mul_f32_e32 v10, v10, v217
	v_mul_f32_e32 v11, v11, v217
	v_mul_f32_e32 v12, v12, v217
	v_mul_f32_e32 v13, v13, v217
	v_mul_f32_e32 v14, v14, v217
	v_mul_f32_e32 v15, v15, v217
	v_mul_f32_e32 v16, v16, v217
	v_mul_f32_e32 v17, v17, v217
	v_mul_f32_e32 v18, v18, v217
	v_mul_f32_e32 v19, v19, v217
	v_mul_f32_e32 v20, v20, v217
	v_mul_f32_e32 v21, v21, v217
	v_mul_f32_e32 v22, v22, v217
	v_mul_f32_e32 v23, v23, v217
	v_mul_f32_e32 v24, v24, v217
	v_mul_f32_e32 v25, v25, v217
	v_mul_f32_e32 v26, v26, v217
	v_mul_f32_e32 v27, v27, v217
	v_mul_f32_e32 v28, v28, v217
	v_mul_f32_e32 v29, v29, v217
	v_mul_f32_e32 v30, v30, v217
	v_mul_f32_e32 v31, v31, v217
	v_mul_f32_e32 v32, v32, v217
	v_mul_f32_e32 v33, v33, v217
.Lna_nr_c0:
	s_waitcnt lgkmcnt(0)
	s_barrier
	ds_read_b128 v[146:149], v200 offset:0
	ds_read_b128 v[150:153], v200 offset:4608
	ds_read_b128 v[154:157], v200 offset:32
	ds_read_b128 v[158:161], v200 offset:4640
	v_exp_f32_e32 v66, v66
	v_exp_f32_e32 v67, v67
	v_exp_f32_e32 v68, v68
	v_exp_f32_e32 v69, v69
	s_waitcnt lgkmcnt(2)
	v_mfma_f32_32x32x16_bf16 v[34:49], v[146:149], v[98:101], v[114:129]
	ds_read_b128 v[146:149], v200 offset:64
	v_add_f32_e32 v213, v213, v66
	v_add_f32_e32 v214, v214, v67
	v_add_f32_e32 v178, v178, v68
	v_add_f32_e32 v179, v179, v69
	v_exp_f32_e32 v70, v70
	v_exp_f32_e32 v71, v71
	v_mfma_f32_32x32x16_bf16 v[50:65], v[150:153], v[98:101], v[130:145]
	ds_read_b128 v[150:153], v200 offset:4672
	v_exp_f32_e32 v72, v72
	v_exp_f32_e32 v73, v73
	v_add_f32_e32 v213, v213, v70
	v_add_f32_e32 v214, v214, v71
	v_add_f32_e32 v178, v178, v72
	s_waitcnt lgkmcnt(2)
	v_mfma_f32_32x32x16_bf16 v[34:49], v[154:157], v[102:105], v[34:49]
	ds_read_b128 v[154:157], v200 offset:96
	v_add_f32_e32 v179, v179, v73
	v_cvt_pk_bf16_f32 v66, v66, v67
	v_cvt_pk_bf16_f32 v67, v68, v69
	v_cvt_pk_bf16_f32 v68, v70, v71
	v_cvt_pk_bf16_f32 v69, v72, v73
	v_exp_f32_e32 v74, v74
	v_exp_f32_e32 v75, v75
	v_mfma_f32_32x32x16_bf16 v[50:65], v[158:161], v[102:105], v[50:65]
	ds_read_b128 v[158:161], v200 offset:4704
	v_exp_f32_e32 v76, v76
	v_exp_f32_e32 v77, v77
	v_add_f32_e32 v213, v213, v74
	v_add_f32_e32 v214, v214, v75
	v_add_f32_e32 v178, v178, v76
	s_waitcnt lgkmcnt(2)
	v_mfma_f32_32x32x16_bf16 v[34:49], v[146:149], v[106:109], v[34:49]
	ds_read_b64 v[162:163], v202 offset:8704
	ds_read_b64 v[164:165], v202 offset:8720
	v_add_f32_e32 v179, v179, v77
	v_exp_f32_e32 v78, v78
	v_exp_f32_e32 v79, v79
	v_exp_f32_e32 v80, v80
	v_mfma_f32_32x32x16_bf16 v[50:65], v[150:153], v[106:109], v[50:65]
	ds_read_b64 v[166:167], v202 offset:13056
	ds_read_b64 v[168:169], v202 offset:13072
	v_exp_f32_e32 v81, v81
	v_add_f32_e32 v213, v213, v78
	v_add_f32_e32 v214, v214, v79
	v_add_f32_e32 v178, v178, v80
	v_add_f32_e32 v179, v179, v81
	v_cvt_pk_bf16_f32 v74, v74, v75
	v_cvt_pk_bf16_f32 v75, v76, v77
	s_waitcnt lgkmcnt(4)
	v_mfma_f32_32x32x16_bf16 v[34:49], v[154:157], v[110:113], v[34:49]
	ds_read_b64 v[170:171], v202 offset:8736
	ds_read_b64 v[172:173], v202 offset:8752
	v_cvt_pk_bf16_f32 v76, v78, v79
	v_cvt_pk_bf16_f32 v77, v80, v81
	v_exp_f32_e32 v82, v82
	v_exp_f32_e32 v83, v83
	v_exp_f32_e32 v84, v84
	v_mfma_f32_32x32x16_bf16 v[50:65], v[158:161], v[110:113], v[50:65]
	ds_read_b64 v[174:175], v202 offset:13088
	ds_read_b64 v[176:177], v202 offset:13104
	v_exp_f32_e32 v85, v85
	v_add_f32_e32 v213, v213, v82
	v_add_f32_e32 v214, v214, v83
	v_add_f32_e32 v178, v178, v84
	v_add_f32_e32 v179, v179, v85
	v_exp_f32_e32 v86, v86
	s_waitcnt lgkmcnt(6)
	v_mfma_f32_32x32x16_bf16 v[2:17], v[162:165], v[66:69], v[2:17]
	ds_read_b64 v[162:163], v202 offset:8768
	ds_read_b64 v[164:165], v202 offset:8784
	v_exp_f32_e32 v87, v87
	v_exp_f32_e32 v88, v88
	v_exp_f32_e32 v89, v89
	v_add_f32_e32 v213, v213, v86
	s_waitcnt lgkmcnt(6)
	v_mfma_f32_32x32x16_bf16 v[18:33], v[166:169], v[66:69], v[18:33]
	ds_read_b64 v[166:167], v202 offset:13120
	ds_read_b64 v[168:169], v202 offset:13136
	v_add_f32_e32 v214, v214, v87
	v_add_f32_e32 v178, v178, v88
	v_add_f32_e32 v179, v179, v89
	v_cvt_pk_bf16_f32 v82, v82, v83
	v_cvt_pk_bf16_f32 v83, v84, v85
	v_cvt_pk_bf16_f32 v84, v86, v87
	v_cvt_pk_bf16_f32 v85, v88, v89
	v_exp_f32_e32 v90, v90
	s_waitcnt lgkmcnt(6)
	v_mfma_f32_32x32x16_bf16 v[2:17], v[170:173], v[74:77], v[2:17]
	ds_read_b64 v[170:171], v202 offset:8800
	ds_read_b64 v[172:173], v202 offset:8816
	v_exp_f32_e32 v91, v91
	v_exp_f32_e32 v92, v92
	v_exp_f32_e32 v93, v93
	s_waitcnt lgkmcnt(6)
	v_mfma_f32_32x32x16_bf16 v[18:33], v[174:177], v[74:77], v[18:33]
	ds_read_b64 v[174:175], v202 offset:13152
	ds_read_b64 v[176:177], v202 offset:13168
	s_waitcnt vmcnt(1)
	ds_write_b128 v204, v[230:233] offset:9216
	ds_write_b64 v205, v[234:235] offset:0
	ds_write_b64 v205, v[236:237] offset:8
	v_add_f32_e32 v213, v213, v90
	v_add_f32_e32 v214, v214, v91
	v_add_f32_e32 v178, v178, v92
	v_add_f32_e32 v179, v179, v93
	v_exp_f32_e32 v94, v94
	v_exp_f32_e32 v95, v95
	s_waitcnt lgkmcnt(9)
	v_mfma_f32_32x32x16_bf16 v[2:17], v[162:165], v[82:85], v[2:17]
	v_exp_f32_e32 v96, v96
	v_exp_f32_e32 v97, v97
	v_add_f32_e32 v213, v213, v94
	v_add_f32_e32 v214, v214, v95
	v_add_f32_e32 v178, v178, v96
	v_add_f32_e32 v179, v179, v97
	s_waitcnt lgkmcnt(7)
	v_mfma_f32_32x32x16_bf16 v[18:33], v[166:169], v[82:85], v[18:33]
	v_cvt_pk_bf16_f32 v90, v90, v91
	v_cvt_pk_bf16_f32 v91, v92, v93
	v_cvt_pk_bf16_f32 v92, v94, v95
	v_cvt_pk_bf16_f32 v93, v96, v97
	v_max3_f32 v216, v34, v35, v36
	v_max3_f32 v217, v50, v51, v52
	v_max3_f32 v216, v216, v37, v38
	s_waitcnt lgkmcnt(5)
	v_mfma_f32_32x32x16_bf16 v[2:17], v[170:173], v[90:93], v[2:17]
	v_max3_f32 v217, v217, v53, v54
	v_max3_f32 v216, v216, v39, v40
	v_max3_f32 v217, v217, v55, v56
	v_max3_f32 v216, v216, v41, v42
	v_max3_f32 v217, v217, v57, v58
	v_max3_f32 v216, v216, v43, v44
	v_max3_f32 v217, v217, v59, v60
	v_max3_f32 v216, v216, v45, v46
	s_waitcnt lgkmcnt(3)
	v_mfma_f32_32x32x16_bf16 v[18:33], v[174:177], v[90:93], v[18:33]
	v_max3_f32 v217, v217, v61, v62
	v_max3_f32 v216, v216, v47, v48
	v_max3_f32 v217, v217, v63, v64
	v_max_f32_e32 v216, v216, v49
	v_max_f32_e32 v217, v217, v65
	v_max_f32_e32 v216, v216, v217
	v_cmp_lt_f32_e32 vcc, 4.0, v216
	s_cbranch_vccz .Lna_nr_c1
	v_mov_b32_e32 v217, v216
	s_nop 1
	v_permlane32_swap_b32_e32 v216, v217
	v_max_f32_e32 v215, v216, v217
	s_nop 15
	v_max_f32_e32 v216, v215, v220
	v_exp_f32_e64 v217, -v216
	v_add_f32_e32 v212, v212, v216
	v_and_b32_e32 v217, v217, v221
	v_sub_f32_e32 v34, v34, v216
	v_sub_f32_e32 v35, v35, v216
	v_sub_f32_e32 v36, v36, v216
	v_sub_f32_e32 v37, v37, v216
	v_sub_f32_e32 v38, v38, v216
	v_sub_f32_e32 v39, v39, v216
	v_sub_f32_e32 v40, v40, v216
	v_sub_f32_e32 v41, v41, v216
	v_sub_f32_e32 v42, v42, v216
	v_sub_f32_e32 v43, v43, v216
	v_sub_f32_e32 v44, v44, v216
	v_sub_f32_e32 v45, v45, v216
	v_sub_f32_e32 v46, v46, v216
	v_sub_f32_e32 v47, v47, v216
	v_sub_f32_e32 v48, v48, v216
	v_sub_f32_e32 v49, v49, v216
	v_sub_f32_e32 v50, v50, v216
	v_sub_f32_e32 v51, v51, v216
	v_sub_f32_e32 v52, v52, v216
	v_sub_f32_e32 v53, v53, v216
	v_sub_f32_e32 v54, v54, v216
	v_sub_f32_e32 v55, v55, v216
	v_sub_f32_e32 v56, v56, v216
	v_sub_f32_e32 v57, v57, v216
	v_sub_f32_e32 v58, v58, v216
	v_sub_f32_e32 v59, v59, v216
	v_sub_f32_e32 v60, v60, v216
	v_sub_f32_e32 v61, v61, v216
	v_sub_f32_e32 v62, v62, v216
	v_sub_f32_e32 v63, v63, v216
	v_sub_f32_e32 v64, v64, v216
	v_sub_f32_e32 v65, v65, v216
	v_sub_f32_e32 v114, v114, v216
	v_sub_f32_e32 v115, v115, v216
	v_sub_f32_e32 v116, v116, v216
	v_sub_f32_e32 v117, v117, v216
	v_sub_f32_e32 v118, v118, v216
	v_sub_f32_e32 v119, v119, v216
	v_sub_f32_e32 v120, v120, v216
	v_sub_f32_e32 v121, v121, v216
	v_sub_f32_e32 v122, v122, v216
	v_sub_f32_e32 v123, v123, v216
	v_sub_f32_e32 v124, v124, v216
	v_sub_f32_e32 v125, v125, v216
	v_sub_f32_e32 v126, v126, v216
	v_sub_f32_e32 v127, v127, v216
	v_sub_f32_e32 v128, v128, v216
	v_sub_f32_e32 v129, v129, v216
	v_sub_f32_e32 v130, v130, v216
	v_sub_f32_e32 v131, v131, v216
	v_sub_f32_e32 v132, v132, v216
	v_sub_f32_e32 v133, v133, v216
	v_sub_f32_e32 v134, v134, v216
	v_sub_f32_e32 v135, v135, v216
	v_sub_f32_e32 v136, v136, v216
	v_sub_f32_e32 v137, v137, v216
	v_sub_f32_e32 v138, v138, v216
	v_sub_f32_e32 v139, v139, v216
	v_sub_f32_e32 v140, v140, v216
	v_sub_f32_e32 v141, v141, v216
	v_sub_f32_e32 v142, v142, v216
	v_sub_f32_e32 v143, v143, v216
	v_sub_f32_e32 v144, v144, v216
	v_sub_f32_e32 v145, v145, v216
	v_mul_f32_e32 v213, v213, v217
	v_mul_f32_e32 v214, v214, v217
	v_mul_f32_e32 v178, v178, v217
	v_mul_f32_e32 v179, v179, v217
	v_mul_f32_e32 v2, v2, v217
	v_mul_f32_e32 v3, v3, v217
	v_mul_f32_e32 v4, v4, v217
	v_mul_f32_e32 v5, v5, v217
	v_mul_f32_e32 v6, v6, v217
	v_mul_f32_e32 v7, v7, v217
	v_mul_f32_e32 v8, v8, v217
	v_mul_f32_e32 v9, v9, v217
	v_mul_f32_e32 v10, v10, v217
	v_mul_f32_e32 v11, v11, v217
	v_mul_f32_e32 v12, v12, v217
	v_mul_f32_e32 v13, v13, v217
	v_mul_f32_e32 v14, v14, v217
	v_mul_f32_e32 v15, v15, v217
	v_mul_f32_e32 v16, v16, v217
	v_mul_f32_e32 v17, v17, v217
	v_mul_f32_e32 v18, v18, v217
	v_mul_f32_e32 v19, v19, v217
	v_mul_f32_e32 v20, v20, v217
	v_mul_f32_e32 v21, v21, v217
	v_mul_f32_e32 v22, v22, v217
	v_mul_f32_e32 v23, v23, v217
	v_mul_f32_e32 v24, v24, v217
	v_mul_f32_e32 v25, v25, v217
	v_mul_f32_e32 v26, v26, v217
	v_mul_f32_e32 v27, v27, v217
	v_mul_f32_e32 v28, v28, v217
	v_mul_f32_e32 v29, v29, v217
	v_mul_f32_e32 v30, v30, v217
	v_mul_f32_e32 v31, v31, v217
	v_mul_f32_e32 v32, v32, v217
	v_mul_f32_e32 v33, v33, v217
.Lna_nr_c1:
	s_waitcnt lgkmcnt(0)
	s_barrier
	ds_read_b128 v[146:149], v200 offset:9216
	ds_read_b128 v[150:153], v200 offset:13824
	ds_read_b128 v[154:157], v200 offset:9248
	ds_read_b128 v[158:161], v200 offset:13856
	v_exp_f32_e32 v34, v34
	v_exp_f32_e32 v35, v35
	v_exp_f32_e32 v36, v36
	v_exp_f32_e32 v37, v37
	s_waitcnt lgkmcnt(2)
	v_mfma_f32_32x32x16_bf16 v[66:81], v[146:149], v[98:101], v[114:129]
	ds_read_b128 v[146:149], v200 offset:9280
	v_add_f32_e32 v213, v213, v34
	v_add_f32_e32 v214, v214, v35
	v_add_f32_e32 v178, v178, v36
	v_add_f32_e32 v179, v179, v37
	v_exp_f32_e32 v38, v38
	v_exp_f32_e32 v39, v39
	v_mfma_f32_32x32x16_bf16 v[82:97], v[150:153], v[98:101], v[130:145]
	ds_read_b128 v[150:153], v200 offset:13888
	v_exp_f32_e32 v40, v40
	v_exp_f32_e32 v41, v41
	v_add_f32_e32 v213, v213, v38
	v_add_f32_e32 v214, v214, v39
	v_add_f32_e32 v178, v178, v40
	s_waitcnt lgkmcnt(2)
	v_mfma_f32_32x32x16_bf16 v[66:81], v[154:157], v[102:105], v[66:81]
	ds_read_b128 v[154:157], v200 offset:9312
	v_add_f32_e32 v179, v179, v41
	v_cvt_pk_bf16_f32 v34, v34, v35
	v_cvt_pk_bf16_f32 v35, v36, v37
	v_cvt_pk_bf16_f32 v36, v38, v39
	v_cvt_pk_bf16_f32 v37, v40, v41
	v_exp_f32_e32 v42, v42
	v_exp_f32_e32 v43, v43
	v_mfma_f32_32x32x16_bf16 v[82:97], v[158:161], v[102:105], v[82:97]
	ds_read_b128 v[158:161], v200 offset:13920
	v_exp_f32_e32 v44, v44
	v_exp_f32_e32 v45, v45
	v_add_f32_e32 v213, v213, v42
	v_add_f32_e32 v214, v214, v43
	v_add_f32_e32 v178, v178, v44
	s_waitcnt lgkmcnt(2)
	v_mfma_f32_32x32x16_bf16 v[66:81], v[146:149], v[106:109], v[66:81]
	ds_read_b64 v[162:163], v202 offset:0
	ds_read_b64 v[164:165], v202 offset:16
	v_add_f32_e32 v179, v179, v45
	v_exp_f32_e32 v46, v46
	v_exp_f32_e32 v47, v47
	v_exp_f32_e32 v48, v48
	v_mfma_f32_32x32x16_bf16 v[82:97], v[150:153], v[106:109], v[82:97]
	ds_read_b64 v[166:167], v202 offset:4352
	ds_read_b64 v[168:169], v202 offset:4368
	v_exp_f32_e32 v49, v49
	v_add_f32_e32 v213, v213, v46
	v_add_f32_e32 v214, v214, v47
	v_add_f32_e32 v178, v178, v48
	v_add_f32_e32 v179, v179, v49
	v_cvt_pk_bf16_f32 v42, v42, v43
	v_cvt_pk_bf16_f32 v43, v44, v45
	s_waitcnt lgkmcnt(4)
	v_mfma_f32_32x32x16_bf16 v[66:81], v[154:157], v[110:113], v[66:81]
	ds_read_b64 v[170:171], v202 offset:32
	ds_read_b64 v[172:173], v202 offset:48
	v_cvt_pk_bf16_f32 v44, v46, v47
	v_cvt_pk_bf16_f32 v45, v48, v49
	v_exp_f32_e32 v50, v50
	v_exp_f32_e32 v51, v51
	v_exp_f32_e32 v52, v52
	v_mfma_f32_32x32x16_bf16 v[82:97], v[158:161], v[110:113], v[82:97]
	ds_read_b64 v[174:175], v202 offset:4384
	ds_read_b64 v[176:177], v202 offset:4400
	v_exp_f32_e32 v53, v53
	v_add_f32_e32 v213, v213, v50
	v_add_f32_e32 v214, v214, v51
	v_add_f32_e32 v178, v178, v52
	v_add_f32_e32 v179, v179, v53
	v_exp_f32_e32 v54, v54
	s_waitcnt lgkmcnt(6)
	v_mfma_f32_32x32x16_bf16 v[2:17], v[162:165], v[34:37], v[2:17]
	ds_read_b64 v[162:163], v202 offset:64
	ds_read_b64 v[164:165], v202 offset:80
	v_exp_f32_e32 v55, v55
	v_exp_f32_e32 v56, v56
	v_exp_f32_e32 v57, v57
	v_add_f32_e32 v213, v213, v54
	s_waitcnt lgkmcnt(6)
	v_mfma_f32_32x32x16_bf16 v[18:33], v[166:169], v[34:37], v[18:33]
	ds_read_b64 v[166:167], v202 offset:4416
	ds_read_b64 v[168:169], v202 offset:4432
	v_add_f32_e32 v214, v214, v55
	v_add_f32_e32 v178, v178, v56
	v_add_f32_e32 v179, v179, v57
	v_cvt_pk_bf16_f32 v50, v50, v51
	v_cvt_pk_bf16_f32 v51, v52, v53
	v_cvt_pk_bf16_f32 v52, v54, v55
	v_cvt_pk_bf16_f32 v53, v56, v57
	v_exp_f32_e32 v58, v58
	s_waitcnt lgkmcnt(6)
	v_mfma_f32_32x32x16_bf16 v[2:17], v[170:173], v[42:45], v[2:17]
	ds_read_b64 v[170:171], v202 offset:96
	ds_read_b64 v[172:173], v202 offset:112
	v_exp_f32_e32 v59, v59
	v_exp_f32_e32 v60, v60
	v_exp_f32_e32 v61, v61
	s_waitcnt lgkmcnt(6)
	v_mfma_f32_32x32x16_bf16 v[18:33], v[174:177], v[42:45], v[18:33]
	ds_read_b64 v[174:175], v202 offset:4448
	ds_read_b64 v[176:177], v202 offset:4464
	s_waitcnt vmcnt(0)
	ds_write_b64 v205, v[192:193] offset:8704
	ds_write_b64 v205, v[194:195] offset:8712
	v_add_f32_e32 v213, v213, v58
	v_add_f32_e32 v214, v214, v59
	v_add_f32_e32 v178, v178, v60
	v_add_f32_e32 v179, v179, v61
	v_exp_f32_e32 v62, v62
	v_exp_f32_e32 v63, v63
	s_waitcnt lgkmcnt(8)
	v_mfma_f32_32x32x16_bf16 v[2:17], v[162:165], v[50:53], v[2:17]
	v_exp_f32_e32 v64, v64
	v_exp_f32_e32 v65, v65
	v_add_f32_e32 v213, v213, v62
	v_add_f32_e32 v214, v214, v63
	v_add_f32_e32 v178, v178, v64
	v_add_f32_e32 v179, v179, v65
	s_waitcnt lgkmcnt(6)
	v_mfma_f32_32x32x16_bf16 v[18:33], v[166:169], v[50:53], v[18:33]
	v_cvt_pk_bf16_f32 v58, v58, v59
	v_cvt_pk_bf16_f32 v59, v60, v61
	v_cvt_pk_bf16_f32 v60, v62, v63
	v_cvt_pk_bf16_f32 v61, v64, v65
	v_max3_f32 v216, v66, v67, v68
	v_max3_f32 v217, v82, v83, v84
	v_max3_f32 v216, v216, v69, v70
	s_waitcnt lgkmcnt(4)
	v_mfma_f32_32x32x16_bf16 v[2:17], v[170:173], v[58:61], v[2:17]
	v_max3_f32 v217, v217, v85, v86
	v_max3_f32 v216, v216, v71, v72
	v_max3_f32 v217, v217, v87, v88
	v_max3_f32 v216, v216, v73, v74
	v_max3_f32 v217, v217, v89, v90
	v_max3_f32 v216, v216, v75, v76
	v_max3_f32 v217, v217, v91, v92
	v_max3_f32 v216, v216, v77, v78
	s_waitcnt lgkmcnt(2)
	v_mfma_f32_32x32x16_bf16 v[18:33], v[174:177], v[58:61], v[18:33]
	v_max3_f32 v217, v217, v93, v94
	v_max3_f32 v216, v216, v79, v80
	v_max3_f32 v217, v217, v95, v96
	v_max_f32_e32 v216, v216, v81
	v_max_f32_e32 v217, v217, v97
	v_max_f32_e32 v216, v216, v217
	v_cmp_lt_f32_e32 vcc, 4.0, v216
	s_cbranch_vccz .Lna_nr_c2
	v_mov_b32_e32 v217, v216
	s_nop 1
	v_permlane32_swap_b32_e32 v216, v217
	v_max_f32_e32 v215, v216, v217
	s_nop 15
	v_max_f32_e32 v216, v215, v220
	v_exp_f32_e64 v217, -v216
	v_add_f32_e32 v212, v212, v216
	v_and_b32_e32 v217, v217, v221
	v_sub_f32_e32 v66, v66, v216
	v_sub_f32_e32 v67, v67, v216
	v_sub_f32_e32 v68, v68, v216
	v_sub_f32_e32 v69, v69, v216
	v_sub_f32_e32 v70, v70, v216
	v_sub_f32_e32 v71, v71, v216
	v_sub_f32_e32 v72, v72, v216
	v_sub_f32_e32 v73, v73, v216
	v_sub_f32_e32 v74, v74, v216
	v_sub_f32_e32 v75, v75, v216
	v_sub_f32_e32 v76, v76, v216
	v_sub_f32_e32 v77, v77, v216
	v_sub_f32_e32 v78, v78, v216
	v_sub_f32_e32 v79, v79, v216
	v_sub_f32_e32 v80, v80, v216
	v_sub_f32_e32 v81, v81, v216
	v_sub_f32_e32 v82, v82, v216
	v_sub_f32_e32 v83, v83, v216
	v_sub_f32_e32 v84, v84, v216
	v_sub_f32_e32 v85, v85, v216
	v_sub_f32_e32 v86, v86, v216
	v_sub_f32_e32 v87, v87, v216
	v_sub_f32_e32 v88, v88, v216
	v_sub_f32_e32 v89, v89, v216
	v_sub_f32_e32 v90, v90, v216
	v_sub_f32_e32 v91, v91, v216
	v_sub_f32_e32 v92, v92, v216
	v_sub_f32_e32 v93, v93, v216
	v_sub_f32_e32 v94, v94, v216
	v_sub_f32_e32 v95, v95, v216
	v_sub_f32_e32 v96, v96, v216
	v_sub_f32_e32 v97, v97, v216
	v_sub_f32_e32 v114, v114, v216
	v_sub_f32_e32 v115, v115, v216
	v_sub_f32_e32 v116, v116, v216
	v_sub_f32_e32 v117, v117, v216
	v_sub_f32_e32 v118, v118, v216
	v_sub_f32_e32 v119, v119, v216
	v_sub_f32_e32 v120, v120, v216
	v_sub_f32_e32 v121, v121, v216
	v_sub_f32_e32 v122, v122, v216
	v_sub_f32_e32 v123, v123, v216
	v_sub_f32_e32 v124, v124, v216
	v_sub_f32_e32 v125, v125, v216
	v_sub_f32_e32 v126, v126, v216
	v_sub_f32_e32 v127, v127, v216
	v_sub_f32_e32 v128, v128, v216
	v_sub_f32_e32 v129, v129, v216
	v_sub_f32_e32 v130, v130, v216
	v_sub_f32_e32 v131, v131, v216
	v_sub_f32_e32 v132, v132, v216
	v_sub_f32_e32 v133, v133, v216
	v_sub_f32_e32 v134, v134, v216
	v_sub_f32_e32 v135, v135, v216
	v_sub_f32_e32 v136, v136, v216
	v_sub_f32_e32 v137, v137, v216
	v_sub_f32_e32 v138, v138, v216
	v_sub_f32_e32 v139, v139, v216
	v_sub_f32_e32 v140, v140, v216
	v_sub_f32_e32 v141, v141, v216
	v_sub_f32_e32 v142, v142, v216
	v_sub_f32_e32 v143, v143, v216
	v_sub_f32_e32 v144, v144, v216
	v_sub_f32_e32 v145, v145, v216
	v_mul_f32_e32 v213, v213, v217
	v_mul_f32_e32 v214, v214, v217
	v_mul_f32_e32 v178, v178, v217
	v_mul_f32_e32 v179, v179, v217
	v_mul_f32_e32 v2, v2, v217
	v_mul_f32_e32 v3, v3, v217
	v_mul_f32_e32 v4, v4, v217
	v_mul_f32_e32 v5, v5, v217
	v_mul_f32_e32 v6, v6, v217
	v_mul_f32_e32 v7, v7, v217
	v_mul_f32_e32 v8, v8, v217
	v_mul_f32_e32 v9, v9, v217
	v_mul_f32_e32 v10, v10, v217
	v_mul_f32_e32 v11, v11, v217
	v_mul_f32_e32 v12, v12, v217
	v_mul_f32_e32 v13, v13, v217
	v_mul_f32_e32 v14, v14, v217
	v_mul_f32_e32 v15, v15, v217
	v_mul_f32_e32 v16, v16, v217
	v_mul_f32_e32 v17, v17, v217
	v_mul_f32_e32 v18, v18, v217
	v_mul_f32_e32 v19, v19, v217
	v_mul_f32_e32 v20, v20, v217
	v_mul_f32_e32 v21, v21, v217
	v_mul_f32_e32 v22, v22, v217
	v_mul_f32_e32 v23, v23, v217
	v_mul_f32_e32 v24, v24, v217
	v_mul_f32_e32 v25, v25, v217
	v_mul_f32_e32 v26, v26, v217
	v_mul_f32_e32 v27, v27, v217
	v_mul_f32_e32 v28, v28, v217
	v_mul_f32_e32 v29, v29, v217
	v_mul_f32_e32 v30, v30, v217
	v_mul_f32_e32 v31, v31, v217
	v_mul_f32_e32 v32, v32, v217
	v_mul_f32_e32 v33, v33, v217

.Lna_nopf:
	v_exp_f32_e32 v66, v66
	v_exp_f32_e32 v67, v67
	v_exp_f32_e32 v68, v68
	v_exp_f32_e32 v69, v69
	v_add_f32_e32 v213, v213, v66
	v_add_f32_e32 v214, v214, v67
	v_add_f32_e32 v178, v178, v68
	v_add_f32_e32 v179, v179, v69
	v_exp_f32_e32 v70, v70
	ds_read_b64 v[162:163], v202 offset:8704
	ds_read_b64 v[164:165], v202 offset:8720
	ds_read_b64 v[166:167], v202 offset:13056
	ds_read_b64 v[168:169], v202 offset:13072
	ds_read_b64 v[170:171], v202 offset:8736
	ds_read_b64 v[172:173], v202 offset:8752
	ds_read_b64 v[174:175], v202 offset:13088
	ds_read_b64 v[176:177], v202 offset:13104
	v_exp_f32_e32 v71, v71
	v_exp_f32_e32 v72, v72
	v_exp_f32_e32 v73, v73
	v_add_f32_e32 v213, v213, v70
	v_add_f32_e32 v214, v214, v71
	v_add_f32_e32 v178, v178, v72
	v_add_f32_e32 v179, v179, v73
	v_cvt_pk_bf16_f32 v66, v66, v67
	v_cvt_pk_bf16_f32 v67, v68, v69
	v_cvt_pk_bf16_f32 v68, v70, v71
	v_cvt_pk_bf16_f32 v69, v72, v73
	s_waitcnt lgkmcnt(6)
	s_nop 0
	v_mfma_f32_32x32x16_bf16 v[2:17], v[162:165], v[66:69], v[2:17]
	ds_read_b64 v[162:163], v202 offset:8768
	ds_read_b64 v[164:165], v202 offset:8784
	s_waitcnt lgkmcnt(6)
	v_mfma_f32_32x32x16_bf16 v[18:33], v[166:169], v[66:69], v[18:33]
	ds_read_b64 v[166:167], v202 offset:13120
	ds_read_b64 v[168:169], v202 offset:13136
	v_exp_f32_e32 v74, v74
	v_exp_f32_e32 v75, v75
	v_exp_f32_e32 v76, v76
	v_exp_f32_e32 v77, v77
	v_add_f32_e32 v213, v213, v74
	v_add_f32_e32 v214, v214, v75
	v_add_f32_e32 v178, v178, v76
	v_add_f32_e32 v179, v179, v77
	v_exp_f32_e32 v78, v78
	v_exp_f32_e32 v79, v79
	v_exp_f32_e32 v80, v80
	v_exp_f32_e32 v81, v81
	v_add_f32_e32 v213, v213, v78
	v_add_f32_e32 v214, v214, v79
	v_add_f32_e32 v178, v178, v80
	v_add_f32_e32 v179, v179, v81
	v_cvt_pk_bf16_f32 v74, v74, v75
	v_cvt_pk_bf16_f32 v75, v76, v77
	v_cvt_pk_bf16_f32 v76, v78, v79
	v_cvt_pk_bf16_f32 v77, v80, v81
	s_waitcnt lgkmcnt(6)
	s_nop 0
	v_mfma_f32_32x32x16_bf16 v[2:17], v[170:173], v[74:77], v[2:17]
	ds_read_b64 v[170:171], v202 offset:8800
	ds_read_b64 v[172:173], v202 offset:8816
	s_waitcnt lgkmcnt(6)
	v_mfma_f32_32x32x16_bf16 v[18:33], v[174:177], v[74:77], v[18:33]
	ds_read_b64 v[174:175], v202 offset:13152
	ds_read_b64 v[176:177], v202 offset:13168
	v_exp_f32_e32 v82, v82
	v_exp_f32_e32 v83, v83
	v_exp_f32_e32 v84, v84
	v_exp_f32_e32 v85, v85
	v_add_f32_e32 v213, v213, v82
	v_add_f32_e32 v214, v214, v83
	v_add_f32_e32 v178, v178, v84
	v_add_f32_e32 v179, v179, v85
	v_exp_f32_e32 v86, v86
	v_exp_f32_e32 v87, v87
	v_exp_f32_e32 v88, v88
	v_exp_f32_e32 v89, v89
	v_add_f32_e32 v213, v213, v86
	v_add_f32_e32 v214, v214, v87
	v_add_f32_e32 v178, v178, v88
	v_add_f32_e32 v179, v179, v89
	v_cvt_pk_bf16_f32 v82, v82, v83
	v_cvt_pk_bf16_f32 v83, v84, v85
	v_cvt_pk_bf16_f32 v84, v86, v87
	v_cvt_pk_bf16_f32 v85, v88, v89
	s_waitcnt lgkmcnt(6)
	s_nop 0
	v_mfma_f32_32x32x16_bf16 v[2:17], v[162:165], v[82:85], v[2:17]
	s_waitcnt lgkmcnt(4)
	v_mfma_f32_32x32x16_bf16 v[18:33], v[166:169], v[82:85], v[18:33]
	v_exp_f32_e32 v90, v90
	v_exp_f32_e32 v91, v91
	v_exp_f32_e32 v92, v92
	v_exp_f32_e32 v93, v93
	v_add_f32_e32 v213, v213, v90
	v_add_f32_e32 v214, v214, v91
	v_add_f32_e32 v178, v178, v92
	v_add_f32_e32 v179, v179, v93
	v_exp_f32_e32 v94, v94
	v_exp_f32_e32 v95, v95
	v_exp_f32_e32 v96, v96
	v_exp_f32_e32 v97, v97
	v_add_f32_e32 v213, v213, v94
	v_add_f32_e32 v214, v214, v95
	v_add_f32_e32 v178, v178, v96
	v_add_f32_e32 v179, v179, v97
	v_cvt_pk_bf16_f32 v90, v90, v91
	v_cvt_pk_bf16_f32 v91, v92, v93
	v_cvt_pk_bf16_f32 v92, v94, v95
	v_cvt_pk_bf16_f32 v93, v96, v97
	s_waitcnt lgkmcnt(2)
	s_nop 0
	v_mfma_f32_32x32x16_bf16 v[2:17], v[170:173], v[90:93], v[2:17]
	s_waitcnt lgkmcnt(0)
	v_mfma_f32_32x32x16_bf16 v[18:33], v[174:177], v[90:93], v[18:33]
	s_waitcnt lgkmcnt(0)
	s_barrier
	v_add_f32_e32 v213, v213, v178
	v_add_f32_e32 v214, v214, v179
	v_add_f32_e32 v213, v213, v214
	v_mov_b32_e32 v217, v213
	s_nop 1
	v_permlane32_swap_b32_e32 v213, v217
	v_add_f32_e32 v216, v213, v217
	v_div_scale_f32 v217, s[36:37], v216, v216, 1.0
	v_rcp_f32_e32 v223, v217
	v_div_scale_f32 v224, vcc, 1.0, v216, 1.0
	v_fma_f32 v225, -v217, v223, 1.0
	v_fmac_f32_e32 v223, v225, v223
	v_mul_f32_e32 v225, v224, v223
	v_fma_f32 v226, -v217, v225, v224
	v_fmac_f32_e32 v225, v226, v223
	v_fma_f32 v217, -v217, v225, v224
	v_div_fmas_f32 v217, v217, v223, v225
	v_div_fixup_f32 v216, v217, v216, 1.0
	s_nop 15
	v_mul_f32_e32 v2, v2, v216
	v_mul_f32_e32 v3, v3, v216
	v_mul_f32_e32 v4, v4, v216
	v_mul_f32_e32 v5, v5, v216
	v_mul_f32_e32 v6, v6, v216
	v_mul_f32_e32 v7, v7, v216
	v_mul_f32_e32 v8, v8, v216
	v_mul_f32_e32 v9, v9, v216
	v_mul_f32_e32 v10, v10, v216
	v_mul_f32_e32 v11, v11, v216
	v_mul_f32_e32 v12, v12, v216
	v_mul_f32_e32 v13, v13, v216
	v_mul_f32_e32 v14, v14, v216
	v_mul_f32_e32 v15, v15, v216
	v_mul_f32_e32 v16, v16, v216
	v_mul_f32_e32 v17, v17, v216
	v_mul_f32_e32 v18, v18, v216
	v_mul_f32_e32 v19, v19, v216
	v_mul_f32_e32 v20, v20, v216
	v_mul_f32_e32 v21, v21, v216
	v_mul_f32_e32 v22, v22, v216
	v_mul_f32_e32 v23, v23, v216
	v_mul_f32_e32 v24, v24, v216
	v_mul_f32_e32 v25, v25, v216
	v_mul_f32_e32 v26, v26, v216
	v_mul_f32_e32 v27, v27, v216
	v_mul_f32_e32 v28, v28, v216
	v_mul_f32_e32 v29, v29, v216
	v_mul_f32_e32 v30, v30, v216
	v_mul_f32_e32 v31, v31, v216
	v_mul_f32_e32 v32, v32, v216
	v_mul_f32_e32 v33, v33, v216
	s_cmpk_lt_i32 s10, 0x200
	s_cbranch_scc1 .Lna_zw9
	s_waitcnt vmcnt(1)
	s_branch .Lna_zw

.Lna_zw:
	v_lshlrev_b32_e32 v223, 16, v146
	v_and_b32_e32 v224, 0xffff0000, v146
	v_lshlrev_b32_e32 v225, 16, v147
	v_and_b32_e32 v226, 0xffff0000, v147
	v_mul_f32_e32 v2, v2, v223
	v_mul_f32_e32 v3, v3, v224
	v_mul_f32_e32 v4, v4, v225
	v_mul_f32_e32 v5, v5, v226
	v_cvt_pk_bf16_f32 v146, v2, v3
	v_cvt_pk_bf16_f32 v147, v4, v5
	global_store_dwordx2 v218, v[146:147], s[46:47] offset:0
	v_lshlrev_b32_e32 v223, 16, v148
	v_and_b32_e32 v224, 0xffff0000, v148
	v_lshlrev_b32_e32 v225, 16, v149
	v_and_b32_e32 v226, 0xffff0000, v149
	v_mul_f32_e32 v6, v6, v223
	v_mul_f32_e32 v7, v7, v224
	v_mul_f32_e32 v8, v8, v225
	v_mul_f32_e32 v9, v9, v226
	v_cvt_pk_bf16_f32 v148, v6, v7
	v_cvt_pk_bf16_f32 v149, v8, v9
	global_store_dwordx2 v218, v[148:149], s[46:47] offset:16
	v_lshlrev_b32_e32 v223, 16, v150
	v_and_b32_e32 v224, 0xffff0000, v150
	v_lshlrev_b32_e32 v225, 16, v151
	v_and_b32_e32 v226, 0xffff0000, v151
	v_mul_f32_e32 v10, v10, v223
	v_mul_f32_e32 v11, v11, v224
	v_mul_f32_e32 v12, v12, v225
	v_mul_f32_e32 v13, v13, v226
	v_cvt_pk_bf16_f32 v150, v10, v11
	v_cvt_pk_bf16_f32 v151, v12, v13
	global_store_dwordx2 v218, v[150:151], s[46:47] offset:32
	v_lshlrev_b32_e32 v223, 16, v152
	v_and_b32_e32 v224, 0xffff0000, v152
	v_lshlrev_b32_e32 v225, 16, v153
	v_and_b32_e32 v226, 0xffff0000, v153
	v_mul_f32_e32 v14, v14, v223
	v_mul_f32_e32 v15, v15, v224
	v_mul_f32_e32 v16, v16, v225
	v_mul_f32_e32 v17, v17, v226
	v_cvt_pk_bf16_f32 v152, v14, v15
	v_cvt_pk_bf16_f32 v153, v16, v17
	global_store_dwordx2 v218, v[152:153], s[46:47] offset:48
	v_lshlrev_b32_e32 v223, 16, v154
	v_and_b32_e32 v224, 0xffff0000, v154
	v_lshlrev_b32_e32 v225, 16, v155
	v_and_b32_e32 v226, 0xffff0000, v155
	v_mul_f32_e32 v18, v18, v223
	v_mul_f32_e32 v19, v19, v224
	v_mul_f32_e32 v20, v20, v225
	v_mul_f32_e32 v21, v21, v226
	v_cvt_pk_bf16_f32 v154, v18, v19
	v_cvt_pk_bf16_f32 v155, v20, v21
	global_store_dwordx2 v218, v[154:155], s[46:47] offset:64
	v_lshlrev_b32_e32 v223, 16, v156
	v_and_b32_e32 v224, 0xffff0000, v156
	v_lshlrev_b32_e32 v225, 16, v157
	v_and_b32_e32 v226, 0xffff0000, v157
	v_mul_f32_e32 v22, v22, v223
	v_mul_f32_e32 v23, v23, v224
	v_mul_f32_e32 v24, v24, v225
	v_mul_f32_e32 v25, v25, v226
	v_cvt_pk_bf16_f32 v156, v22, v23
	v_cvt_pk_bf16_f32 v157, v24, v25
	global_store_dwordx2 v218, v[156:157], s[46:47] offset:80
	v_lshlrev_b32_e32 v223, 16, v158
	v_and_b32_e32 v224, 0xffff0000, v158
	v_lshlrev_b32_e32 v225, 16, v159
	v_and_b32_e32 v226, 0xffff0000, v159
	v_mul_f32_e32 v26, v26, v223
	v_mul_f32_e32 v27, v27, v224
	v_mul_f32_e32 v28, v28, v225
	v_mul_f32_e32 v29, v29, v226
	v_cvt_pk_bf16_f32 v158, v26, v27
	v_cvt_pk_bf16_f32 v159, v28, v29
	global_store_dwordx2 v218, v[158:159], s[46:47] offset:96
	v_lshlrev_b32_e32 v223, 16, v160
	v_and_b32_e32 v224, 0xffff0000, v160
	v_lshlrev_b32_e32 v225, 16, v161
	v_and_b32_e32 v226, 0xffff0000, v161
	v_mul_f32_e32 v30, v30, v223
	v_mul_f32_e32 v31, v31, v224
	v_mul_f32_e32 v32, v32, v225
	v_mul_f32_e32 v33, v33, v226
	v_cvt_pk_bf16_f32 v160, v30, v31
	v_cvt_pk_bf16_f32 v161, v32, v33
	global_store_dwordx2 v218, v[160:161], s[46:47] offset:112
	s_cmpk_lt_i32 s10, 0x200
	s_cbranch_scc0 .Lna_exit
	v_mov_b32_e32 v2, 0
	v_mov_b32_e32 v3, 0
	v_mov_b32_e32 v4, 0
	v_mov_b32_e32 v5, 0
	v_mov_b32_e32 v6, 0
	v_mov_b32_e32 v7, 0
	v_mov_b32_e32 v8, 0
	v_mov_b32_e32 v9, 0
	v_mov_b32_e32 v10, 0
	v_mov_b32_e32 v11, 0
	v_mov_b32_e32 v12, 0
	v_mov_b32_e32 v13, 0
	v_mov_b32_e32 v14, 0
	v_mov_b32_e32 v15, 0
	v_mov_b32_e32 v16, 0
	v_mov_b32_e32 v17, 0
	v_mov_b32_e32 v18, 0
	v_mov_b32_e32 v19, 0
	v_mov_b32_e32 v20, 0
	v_mov_b32_e32 v21, 0
	v_mov_b32_e32 v22, 0
	v_mov_b32_e32 v23, 0
	v_mov_b32_e32 v24, 0
	v_mov_b32_e32 v25, 0
	v_mov_b32_e32 v26, 0
	v_mov_b32_e32 v27, 0
	v_mov_b32_e32 v28, 0
	v_mov_b32_e32 v29, 0
	v_mov_b32_e32 v30, 0
	v_mov_b32_e32 v31, 0
	v_mov_b32_e32 v32, 0
	v_mov_b32_e32 v33, 0
	v_mov_b32_e32 v212, 0
	v_mov_b32_e32 v213, 0
	v_mov_b32_e32 v214, 0
	v_mov_b32_e32 v178, 0
	v_mov_b32_e32 v179, 0
	v_mov_b32_e32 v220, 0xff7fffff
	v_mov_b32_e32 v221, 0
	s_mov_b64 s[26:27], -1
	v_and_b32_e32 v216, 15, v0
	v_bfe_u32 v217, v0, 5, 1
	s_lshl_b32 s36, s11, 4
	v_add_u32_e32 v222, s36, v216
	v_subrev_u32_e32 v223, 8, v222
	v_med3_i32 v223, v223, 0, 48
	v_lshl_add_u32 v224, v217, 2, s66
	v_sub_u32_e32 v224, v224, v223
	v_add_u32_e32 v225, 0, v224
	v_cmp_gt_u32_e32 vcc, 16, v225
	s_nop 1
	v_cndmask_b32_e32 v114, v229, v228, vcc
	v_add_u32_e32 v225, 1, v224
	v_cmp_gt_u32_e32 vcc, 16, v225
	s_nop 1
	v_cndmask_b32_e32 v115, v229, v228, vcc
	v_add_u32_e32 v225, 2, v224
	v_cmp_gt_u32_e32 vcc, 16, v225
	s_nop 1
	v_cndmask_b32_e32 v116, v229, v228, vcc
	v_add_u32_e32 v225, 3, v224
	v_cmp_gt_u32_e32 vcc, 16, v225
	s_nop 1
	v_cndmask_b32_e32 v117, v229, v228, vcc
	v_add_u32_e32 v225, 8, v224
	v_cmp_gt_u32_e32 vcc, 16, v225
	s_nop 1
	v_cndmask_b32_e32 v118, v229, v228, vcc
	v_add_u32_e32 v225, 9, v224
	v_cmp_gt_u32_e32 vcc, 16, v225
	s_nop 1
	v_cndmask_b32_e32 v119, v229, v228, vcc
	v_add_u32_e32 v225, 10, v224
	v_cmp_gt_u32_e32 vcc, 16, v225
	s_nop 1
	v_cndmask_b32_e32 v120, v229, v228, vcc
	v_add_u32_e32 v225, 11, v224
	v_cmp_gt_u32_e32 vcc, 16, v225
	s_nop 1
	v_cndmask_b32_e32 v121, v229, v228, vcc
	v_add_u32_e32 v225, 16, v224
	v_cmp_gt_u32_e32 vcc, 16, v225
	s_nop 1
	v_cndmask_b32_e32 v122, v229, v228, vcc
	v_add_u32_e32 v225, 17, v224
	v_cmp_gt_u32_e32 vcc, 16, v225
	s_nop 1
	v_cndmask_b32_e32 v123, v229, v228, vcc
	v_add_u32_e32 v225, 18, v224
	v_cmp_gt_u32_e32 vcc, 16, v225
	s_nop 1
	v_cndmask_b32_e32 v124, v229, v228, vcc
	v_add_u32_e32 v225, 19, v224
	v_cmp_gt_u32_e32 vcc, 16, v225
	s_nop 1
	v_cndmask_b32_e32 v125, v229, v228, vcc
	v_add_u32_e32 v225, 24, v224
	v_cmp_gt_u32_e32 vcc, 16, v225
	s_nop 1
	v_cndmask_b32_e32 v126, v229, v228, vcc
	v_add_u32_e32 v225, 25, v224
	v_cmp_gt_u32_e32 vcc, 16, v225
	s_nop 1
	v_cndmask_b32_e32 v127, v229, v228, vcc
	v_add_u32_e32 v225, 26, v224
	v_cmp_gt_u32_e32 vcc, 16, v225
	s_nop 1
	v_cndmask_b32_e32 v128, v229, v228, vcc
	v_add_u32_e32 v225, 27, v224
	v_cmp_gt_u32_e32 vcc, 16, v225
	s_nop 1
	v_cndmask_b32_e32 v129, v229, v228, vcc
	s_waitcnt vmcnt(12)
	s_branch .Lna_stage
